# non-temporal (nt) cache policy on once-read streams: f32 weight and cache loads in phase A, x rows in phase A, per-token streams in phase E, final-norm loads and stores, f32 K/V cache stores in the in
# speedup vs baseline: 1.0266x; 1.0266x over previous
.LBB0_59:
	v_lshl_add_u64 v[64:65], v[64:65], 0, v[168:169]
	global_load_dwordx4 v[92:95], v[64:65], off nt
	global_load_dwordx4 v[88:91], v[64:65], off offset:1024 nt
	global_load_dwordx4 v[84:87], v[64:65], off offset:2048 nt
	global_load_dwordx4 v[80:83], v[64:65], off offset:3072 nt
	v_add_co_u32_e32 v72, vcc, s33, v64
	v_lshlrev_b64 v[130:131], 12, v[130:131]
	s_nop 0
	v_addc_co_u32_e32 v73, vcc, 0, v65, vcc
	s_add_u32 s72, s72, 2
	s_addc_u32 s73, s73, 0
	v_lshl_add_u64 v[126:127], v[126:127], 0, s[28:29]
	s_cmp_eq_u32 s72, 8
	s_waitcnt vmcnt(3)
	v_mul_f32_e32 v66, v93, v93
	s_waitcnt vmcnt(2)
	v_mul_f32_e32 v67, v89, v89
	v_fmac_f32_e32 v66, v92, v92
	v_fmac_f32_e32 v67, v88, v88
	v_fmac_f32_e32 v66, v94, v94
	v_fmac_f32_e32 v67, v90, v90
	v_fmac_f32_e32 v66, v95, v95
	v_fmac_f32_e32 v67, v91, v91
	v_add_f32_e32 v66, v66, v67
	s_waitcnt vmcnt(1)
	v_mul_f32_e32 v67, v85, v85
	v_fmac_f32_e32 v67, v84, v84
	v_fmac_f32_e32 v67, v86, v86
	v_fmac_f32_e32 v67, v87, v87
	v_add_f32_e32 v66, v66, v67
	s_waitcnt vmcnt(0)
	v_mul_f32_e32 v67, v81, v81
	v_fmac_f32_e32 v67, v80, v80
	v_fmac_f32_e32 v67, v82, v82
	v_fmac_f32_e32 v67, v83, v83
	v_add_f32_e32 v78, v66, v67
	global_load_dwordx4 v[68:71], v[72:73], off nt
	global_load_dwordx4 v[64:67], v[72:73], off offset:1024 nt
	s_waitcnt vmcnt(1)
	v_mov_b32_e32 v76, v69
	s_waitcnt vmcnt(0)
	v_mov_b32_e32 v77, v65
	v_mov_b32_e32 v74, v68
	v_mov_b32_e32 v75, v64
	v_pk_mul_f32 v[76:77], v[76:77], v[76:77]
	s_nop 0
	v_pk_fma_f32 v[74:75], v[74:75], v[74:75], v[76:77]
	v_mov_b32_e32 v76, v70
	v_mov_b32_e32 v77, v66
	v_pk_fma_f32 v[74:75], v[76:77], v[76:77], v[74:75]
	v_mov_b32_e32 v76, v71
	v_mov_b32_e32 v77, v67
	v_pk_fma_f32 v[74:75], v[76:77], v[76:77], v[74:75]
	s_nop 0
	v_add_f32_e32 v74, v78, v74
	v_add_f32_e32 v179, v74, v75
	global_load_dwordx4 v[76:79], v[72:73], off offset:2048 nt
	s_nop 0
	global_load_dwordx4 v[72:75], v[72:73], off offset:3072 nt
	s_waitcnt vmcnt(1)
	v_mov_b32_e32 v180, v77
	s_waitcnt vmcnt(0)
	v_mov_b32_e32 v181, v73
	v_mov_b32_e32 v128, v76
	v_mov_b32_e32 v129, v72
	v_pk_mul_f32 v[180:181], v[180:181], v[180:181]
	s_nop 0
	v_pk_fma_f32 v[128:129], v[128:129], v[128:129], v[180:181]
	v_mov_b32_e32 v180, v78
	v_mov_b32_e32 v181, v74
	v_pk_fma_f32 v[128:129], v[180:181], v[180:181], v[128:129]
	v_mov_b32_e32 v180, v79
	v_mov_b32_e32 v181, v75
	v_pk_fma_f32 v[128:129], v[180:181], v[180:181], v[128:129]
	s_nop 0
	v_add_f32_e32 v128, v179, v128
	v_add_f32_e32 v128, v128, v129
	ds_bpermute_b32 v129, v134, v128
	s_waitcnt lgkmcnt(0)
	v_add_f32_e32 v128, v128, v129
	ds_bpermute_b32 v129, v135, v128
	s_waitcnt lgkmcnt(0)
	v_add_f32_e32 v128, v128, v129
	ds_bpermute_b32 v129, v136, v128
	s_waitcnt lgkmcnt(0)
	v_add_f32_e32 v128, v128, v129
	ds_bpermute_b32 v129, v137, v128
	s_waitcnt lgkmcnt(0)
	v_add_f32_e32 v128, v128, v129
	ds_bpermute_b32 v129, v138, v128
	s_waitcnt lgkmcnt(0)
	v_add_f32_e32 v128, v128, v129
	ds_bpermute_b32 v129, v139, v128
	s_waitcnt lgkmcnt(0)
	v_add_f32_e32 v128, v128, v129
	v_fmamk_f32 v128, v128, 0x3a000000, v209
	v_cmp_gt_f32_e32 vcc, s80, v128
	v_mul_f32_e32 v129, 0x4b800000, v128
	s_nop 0
	v_cndmask_b32_e32 v128, v128, v129, vcc
	v_rsq_f32_e32 v128, v128
	s_nop 0
	v_mul_f32_e32 v129, 0x45800000, v128
	v_cndmask_b32_e32 v128, v128, v129, vcc
	v_mul_f32_e32 v94, v94, v128
	v_mul_f32_e32 v92, v92, v128
	v_mul_f32_e32 v93, v93, v128
	v_mul_f32_e32 v94, v14, v94
	v_mul_f32_e32 v64, v64, v128
	v_mul_f32_e32 v65, v65, v128
	v_mul_f32_e32 v92, v12, v92
	v_mul_f32_e32 v93, v13, v93
	v_fma_f32 v129, v125, v94, v38
	v_mul_f32_e32 v94, v95, v128
	v_mul_f32_e32 v64, v32, v64
	v_mul_f32_e32 v65, v33, v65
	v_mul_f32_e32 v66, v66, v128
	v_mul_f32_e32 v67, v67, v128
	v_fma_f32 v92, v121, v92, v36
	v_fma_f32 v93, v123, v93, v37
	v_mul_f32_e32 v94, v15, v94
	v_fma_f32 v64, v157, v64, v4
	v_fma_f32 v65, v158, v65, v5
	v_mul_f32_e32 v66, v34, v66
	v_mul_f32_e32 v67, v35, v67
	v_fma_f32 v95, v140, v94, v39
	v_cvt_pk_bf16_f32 v94, v92, v93
	v_lshl_add_u64 v[92:93], v[108:109], 0, v[130:131]
	v_fma_f32 v66, v159, v66, v6
	v_fma_f32 v67, v160, v67, v7
	v_cvt_pk_bf16_f32 v64, v64, v65
	v_cvt_pk_bf16_f32 v65, v66, v67
	global_store_dwordx2 v[92:93], v[64:65], off offset:2560
	v_mul_f32_e32 v64, v76, v128
	v_mul_f32_e32 v65, v77, v128
	v_mul_f32_e32 v64, v44, v64
	v_mul_f32_e32 v65, v45, v65
	v_mul_f32_e32 v66, v78, v128
	v_mul_f32_e32 v67, v79, v128
	v_fma_f32 v64, v161, v64, v8
	v_fma_f32 v65, v162, v65, v9
	v_mul_f32_e32 v66, v46, v66
	v_mul_f32_e32 v67, v47, v67
	v_fma_f32 v66, v163, v66, v10
	v_fma_f32 v67, v164, v67, v11
	v_cvt_pk_bf16_f32 v64, v64, v65
	v_cvt_pk_bf16_f32 v65, v66, v67
	v_mul_f32_e32 v88, v88, v128
	v_mul_f32_e32 v89, v89, v128
	v_mul_f32_e32 v84, v84, v128
	v_mul_f32_e32 v85, v85, v128
	v_mul_f32_e32 v80, v80, v128
	v_mul_f32_e32 v81, v81, v128
	v_mul_f32_e32 v68, v68, v128
	v_mul_f32_e32 v69, v69, v128
	global_store_dwordx2 v[92:93], v[64:65], off offset:3072
	v_mul_f32_e32 v64, v72, v128
	v_mul_f32_e32 v65, v73, v128
	v_mul_f32_e32 v88, v16, v88
	v_mul_f32_e32 v89, v17, v89
	v_mul_f32_e32 v90, v90, v128
	v_mul_f32_e32 v91, v91, v128
	v_mul_f32_e32 v84, v20, v84
	v_mul_f32_e32 v85, v21, v85
	v_mul_f32_e32 v86, v86, v128
	v_mul_f32_e32 v87, v87, v128
	v_mul_f32_e32 v80, v24, v80
	v_mul_f32_e32 v81, v25, v81
	v_mul_f32_e32 v82, v82, v128
	v_mul_f32_e32 v83, v83, v128
	v_mul_f32_e32 v68, v28, v68
	v_mul_f32_e32 v69, v29, v69
	v_mul_f32_e32 v70, v70, v128
	v_mul_f32_e32 v71, v71, v128
	v_mul_f32_e32 v64, v48, v64
	v_mul_f32_e32 v65, v49, v65
	v_mul_f32_e32 v66, v74, v128
	v_mul_f32_e32 v67, v75, v128
	v_fma_f32 v88, v141, v88, v40
	v_fma_f32 v89, v142, v89, v41
	v_mul_f32_e32 v90, v18, v90
	v_mul_f32_e32 v91, v19, v91
	v_fma_f32 v84, v145, v84, v52
	v_fma_f32 v85, v146, v85, v53
	v_mul_f32_e32 v86, v22, v86
	v_mul_f32_e32 v87, v23, v87
	v_fma_f32 v80, v149, v80, v56
	v_fma_f32 v81, v150, v81, v57
	v_mul_f32_e32 v82, v26, v82
	v_mul_f32_e32 v83, v27, v83
	v_fma_f32 v68, v153, v68, v0
	v_fma_f32 v69, v154, v69, v1
	v_mul_f32_e32 v70, v30, v70
	v_mul_f32_e32 v71, v31, v71
	v_fma_f32 v64, v165, v64, v60
	v_fma_f32 v65, v166, v65, v61
	v_mul_f32_e32 v66, v50, v66
	v_mul_f32_e32 v67, v51, v67
	v_cvt_pk_bf16_f32 v95, v129, v95
	global_store_dwordx2 v[92:93], v[94:95], off
	v_fma_f32 v90, v143, v90, v42
	v_fma_f32 v91, v144, v91, v43
	v_cvt_pk_bf16_f32 v88, v88, v89
	v_cvt_pk_bf16_f32 v89, v90, v91
	global_store_dwordx2 v[92:93], v[88:89], off offset:512
	v_fma_f32 v86, v147, v86, v54
	v_fma_f32 v87, v148, v87, v55
	v_cvt_pk_bf16_f32 v84, v84, v85
	v_cvt_pk_bf16_f32 v85, v86, v87
	global_store_dwordx2 v[92:93], v[84:85], off offset:1024
	v_fma_f32 v82, v151, v82, v58
	v_fma_f32 v83, v152, v83, v59
	v_cvt_pk_bf16_f32 v80, v80, v81
	v_cvt_pk_bf16_f32 v81, v82, v83
	global_store_dwordx2 v[92:93], v[80:81], off offset:1536
	v_fma_f32 v70, v155, v70, v2
	v_fma_f32 v71, v156, v71, v3
	v_cvt_pk_bf16_f32 v68, v68, v69
	v_cvt_pk_bf16_f32 v69, v70, v71
	global_store_dwordx2 v[92:93], v[68:69], off offset:2048
	v_fma_f32 v66, v167, v66, v62
	v_fma_f32 v67, v178, v67, v63
	v_cvt_pk_bf16_f32 v64, v64, v65
	v_cvt_pk_bf16_f32 v65, v66, v67
	global_store_dwordx2 v[92:93], v[64:65], off offset:3584
	s_cbranch_scc1 .LBB0_56

.LBB0_66:
	v_lshl_add_u64 v[64:65], v[64:65], 0, v[168:169]
	global_load_dwordx4 v[92:95], v[64:65], off nt
	global_load_dwordx4 v[88:91], v[64:65], off offset:1024 nt
	global_load_dwordx4 v[84:87], v[64:65], off offset:2048 nt
	global_load_dwordx4 v[80:83], v[64:65], off offset:3072 nt
	v_add_co_u32_e32 v72, vcc, s33, v64
	v_lshlrev_b64 v[130:131], 12, v[130:131]
	s_nop 0
	v_addc_co_u32_e32 v73, vcc, 0, v65, vcc
	s_mov_b64 s[18:19], -1
	s_waitcnt vmcnt(3)
	v_mul_f32_e32 v66, v93, v93
	s_waitcnt vmcnt(2)
	v_mul_f32_e32 v67, v89, v89
	v_fmac_f32_e32 v66, v92, v92
	v_fmac_f32_e32 v67, v88, v88
	v_fmac_f32_e32 v66, v94, v94
	v_fmac_f32_e32 v67, v90, v90
	v_fmac_f32_e32 v66, v95, v95
	v_fmac_f32_e32 v67, v91, v91
	v_add_f32_e32 v66, v66, v67
	s_waitcnt vmcnt(1)
	v_mul_f32_e32 v67, v85, v85
	v_fmac_f32_e32 v67, v84, v84
	v_fmac_f32_e32 v67, v86, v86
	v_fmac_f32_e32 v67, v87, v87
	v_add_f32_e32 v66, v66, v67
	s_waitcnt vmcnt(0)
	v_mul_f32_e32 v67, v81, v81
	v_fmac_f32_e32 v67, v80, v80
	v_fmac_f32_e32 v67, v82, v82
	v_fmac_f32_e32 v67, v83, v83
	v_add_f32_e32 v78, v66, v67
	global_load_dwordx4 v[68:71], v[72:73], off nt
	global_load_dwordx4 v[64:67], v[72:73], off offset:1024 nt
	s_waitcnt vmcnt(1)
	v_mov_b32_e32 v76, v69
	s_waitcnt vmcnt(0)
	v_mov_b32_e32 v77, v65
	v_mov_b32_e32 v74, v68
	v_mov_b32_e32 v75, v64
	v_pk_mul_f32 v[76:77], v[76:77], v[76:77]
	s_nop 0
	v_pk_fma_f32 v[74:75], v[74:75], v[74:75], v[76:77]
	v_mov_b32_e32 v76, v70
	v_mov_b32_e32 v77, v66
	v_pk_fma_f32 v[74:75], v[76:77], v[76:77], v[74:75]
	v_mov_b32_e32 v76, v71
	v_mov_b32_e32 v77, v67
	v_pk_fma_f32 v[74:75], v[76:77], v[76:77], v[74:75]
	s_nop 0
	v_add_f32_e32 v74, v78, v74
	v_add_f32_e32 v179, v74, v75
	global_load_dwordx4 v[76:79], v[72:73], off offset:2048 nt
	s_nop 0
	global_load_dwordx4 v[72:75], v[72:73], off offset:3072 nt
	s_waitcnt vmcnt(1)
	v_mov_b32_e32 v182, v77
	s_waitcnt vmcnt(0)
	v_mov_b32_e32 v183, v73
	v_mov_b32_e32 v180, v76
	v_mov_b32_e32 v181, v72
	v_pk_mul_f32 v[182:183], v[182:183], v[182:183]
	s_nop 0
	v_pk_fma_f32 v[180:181], v[180:181], v[180:181], v[182:183]
	v_mov_b32_e32 v182, v78
	v_mov_b32_e32 v183, v74
	v_pk_fma_f32 v[180:181], v[182:183], v[182:183], v[180:181]
	v_mov_b32_e32 v182, v79
	v_mov_b32_e32 v183, v75
	v_pk_fma_f32 v[180:181], v[182:183], v[182:183], v[180:181]
	s_nop 0
	v_add_f32_e32 v179, v179, v180
	v_add_f32_e32 v179, v179, v181
	ds_bpermute_b32 v180, v134, v179
	s_waitcnt lgkmcnt(0)
	v_add_f32_e32 v179, v179, v180
	ds_bpermute_b32 v180, v135, v179
	s_waitcnt lgkmcnt(0)
	v_add_f32_e32 v179, v179, v180
	ds_bpermute_b32 v180, v136, v179
	s_waitcnt lgkmcnt(0)
	v_add_f32_e32 v179, v179, v180
	ds_bpermute_b32 v180, v137, v179
	s_waitcnt lgkmcnt(0)
	v_add_f32_e32 v179, v179, v180
	ds_bpermute_b32 v180, v138, v179
	s_waitcnt lgkmcnt(0)
	v_add_f32_e32 v179, v179, v180
	ds_bpermute_b32 v180, v139, v179
	s_waitcnt lgkmcnt(0)
	v_add_f32_e32 v179, v179, v180
	v_fmamk_f32 v179, v179, 0x3a000000, v209
	v_cmp_gt_f32_e32 vcc, s80, v179
	v_mul_f32_e32 v180, 0x4b800000, v179
	s_nop 0
	v_cndmask_b32_e32 v179, v179, v180, vcc
	v_rsq_f32_e32 v179, v179
	s_nop 0
	v_mul_f32_e32 v180, 0x45800000, v179
	v_cndmask_b32_e32 v179, v179, v180, vcc
	v_mul_f32_e32 v94, v94, v179
	v_mul_f32_e32 v92, v92, v179
	v_mul_f32_e32 v93, v93, v179
	v_mul_f32_e32 v94, v14, v94
	v_mul_f32_e32 v64, v64, v179
	v_mul_f32_e32 v65, v65, v179
	v_mul_f32_e32 v92, v12, v92
	v_mul_f32_e32 v93, v13, v93
	v_fma_f32 v180, v125, v94, v38
	v_mul_f32_e32 v94, v95, v179
	v_mul_f32_e32 v64, v32, v64
	v_mul_f32_e32 v65, v33, v65
	v_mul_f32_e32 v66, v66, v179
	v_mul_f32_e32 v67, v67, v179
	v_fma_f32 v92, v121, v92, v36
	v_fma_f32 v93, v123, v93, v37
	v_mul_f32_e32 v94, v15, v94
	v_fma_f32 v64, v157, v64, v4
	v_fma_f32 v65, v158, v65, v5
	v_mul_f32_e32 v66, v34, v66
	v_mul_f32_e32 v67, v35, v67
	v_fma_f32 v95, v140, v94, v39
	v_cvt_pk_bf16_f32 v94, v92, v93
	v_lshl_add_u64 v[92:93], v[108:109], 0, v[130:131]
	v_fma_f32 v66, v159, v66, v6
	v_fma_f32 v67, v160, v67, v7
	v_cvt_pk_bf16_f32 v64, v64, v65
	v_cvt_pk_bf16_f32 v65, v66, v67
	global_store_dwordx2 v[92:93], v[64:65], off offset:2560
	v_mul_f32_e32 v64, v76, v179
	v_mul_f32_e32 v65, v77, v179
	v_mul_f32_e32 v64, v44, v64
	v_mul_f32_e32 v65, v45, v65
	v_mul_f32_e32 v66, v78, v179
	v_mul_f32_e32 v67, v79, v179
	v_fma_f32 v64, v161, v64, v8
	v_fma_f32 v65, v162, v65, v9
	v_mul_f32_e32 v66, v46, v66
	v_mul_f32_e32 v67, v47, v67
	v_fma_f32 v66, v163, v66, v10
	v_fma_f32 v67, v164, v67, v11
	v_cvt_pk_bf16_f32 v64, v64, v65
	v_cvt_pk_bf16_f32 v65, v66, v67
	global_store_dwordx2 v[92:93], v[64:65], off offset:3072
	v_mul_f32_e32 v64, v72, v179
	v_mul_f32_e32 v65, v73, v179
	v_mul_f32_e32 v88, v88, v179
	v_mul_f32_e32 v89, v89, v179
	v_mul_f32_e32 v84, v84, v179
	v_mul_f32_e32 v85, v85, v179
	v_mul_f32_e32 v80, v80, v179
	v_mul_f32_e32 v81, v81, v179
	v_mul_f32_e32 v68, v68, v179
	v_mul_f32_e32 v69, v69, v179
	v_mul_f32_e32 v64, v48, v64
	v_mul_f32_e32 v65, v49, v65
	v_mul_f32_e32 v66, v74, v179
	v_mul_f32_e32 v67, v75, v179
	v_mul_f32_e32 v88, v16, v88
	v_mul_f32_e32 v89, v17, v89
	v_mul_f32_e32 v90, v90, v179
	v_mul_f32_e32 v91, v91, v179
	v_mul_f32_e32 v84, v20, v84
	v_mul_f32_e32 v85, v21, v85
	v_mul_f32_e32 v86, v86, v179
	v_mul_f32_e32 v87, v87, v179
	v_mul_f32_e32 v80, v24, v80
	v_mul_f32_e32 v81, v25, v81
	v_mul_f32_e32 v82, v82, v179
	v_mul_f32_e32 v83, v83, v179
	v_mul_f32_e32 v68, v28, v68
	v_mul_f32_e32 v69, v29, v69
	v_mul_f32_e32 v70, v70, v179
	v_mul_f32_e32 v71, v71, v179
	v_fma_f32 v64, v165, v64, v60
	v_fma_f32 v65, v166, v65, v61
	v_mul_f32_e32 v66, v50, v66
	v_mul_f32_e32 v67, v51, v67
	v_fma_f32 v88, v141, v88, v40
	v_fma_f32 v89, v142, v89, v41
	v_mul_f32_e32 v90, v18, v90
	v_mul_f32_e32 v91, v19, v91
	v_fma_f32 v84, v145, v84, v52
	v_fma_f32 v85, v146, v85, v53
	v_mul_f32_e32 v86, v22, v86
	v_mul_f32_e32 v87, v23, v87
	v_fma_f32 v80, v149, v80, v56
	v_fma_f32 v81, v150, v81, v57
	v_mul_f32_e32 v82, v26, v82
	v_mul_f32_e32 v83, v27, v83
	v_fma_f32 v68, v153, v68, v0
	v_fma_f32 v69, v154, v69, v1
	v_mul_f32_e32 v70, v30, v70
	v_mul_f32_e32 v71, v31, v71
	v_fma_f32 v66, v167, v66, v62
	v_fma_f32 v67, v178, v67, v63
	v_cvt_pk_bf16_f32 v64, v64, v65
	v_cvt_pk_bf16_f32 v65, v66, v67
	v_lshl_add_u64 v[130:131], v[128:129], 0, 1
	s_andn2_b64 vcc, exec, s[2:3]
	v_cvt_pk_bf16_f32 v95, v180, v95
	global_store_dwordx2 v[92:93], v[94:95], off
	v_fma_f32 v90, v143, v90, v42
	v_fma_f32 v91, v144, v91, v43
	v_cvt_pk_bf16_f32 v88, v88, v89
	v_cvt_pk_bf16_f32 v89, v90, v91
	global_store_dwordx2 v[92:93], v[88:89], off offset:512
	v_fma_f32 v86, v147, v86, v54
	v_fma_f32 v87, v148, v87, v55
	v_cvt_pk_bf16_f32 v84, v84, v85
	v_cvt_pk_bf16_f32 v85, v86, v87
	global_store_dwordx2 v[92:93], v[84:85], off offset:1024
	v_fma_f32 v82, v151, v82, v58
	v_fma_f32 v83, v152, v83, v59
	v_cvt_pk_bf16_f32 v80, v80, v81
	v_cvt_pk_bf16_f32 v81, v82, v83
	global_store_dwordx2 v[92:93], v[80:81], off offset:1536
	v_fma_f32 v70, v155, v70, v2
	v_fma_f32 v71, v156, v71, v3
	v_cvt_pk_bf16_f32 v68, v68, v69
	v_cvt_pk_bf16_f32 v69, v70, v71
	global_store_dwordx2 v[92:93], v[68:69], off offset:2048
	global_store_dwordx2 v[92:93], v[64:65], off offset:3584
	s_cbranch_vccnz .LBB0_68
	v_ashrrev_i32_e32 v131, 31, v130
	v_lshlrev_b64 v[64:65], 13, v[130:131]
	v_lshl_add_u64 v[64:65], s[60:61], 0, v[64:65]
	s_mov_b64 s[18:19], 0

.LBB0_82:
	v_mov_b32_e32 v2, v200
	s_ashr_i32 s61, s60, 31
	v_ashrrev_i32_e32 v0, 5, v2
	v_add_u32_e32 v10, s42, v0
	v_lshlrev_b32_e32 v2, 4, v2
	v_mad_i64_i32 v[0:1], s[10:11], s38, v10, 0
	v_and_b32_e32 v168, 0x1f0, v2
	v_add_u32_e32 v2, 16, v10
	v_add_u32_e32 v8, 32, v10
	v_add_u32_e32 v10, 48, v10
	v_mad_i64_i32 v[2:3], s[12:13], s38, v2, 0
	v_mad_i64_i32 v[8:9], s[12:13], s38, v8, 0
	v_mad_i64_i32 v[10:11], s[12:13], s38, v10, 0
	v_lshl_add_u64 v[0:1], v[0:1], 2, s[40:41]
	s_lshl_b64 s[10:11], s[60:61], 2
	v_lshl_add_u64 v[2:3], v[2:3], 2, s[40:41]
	v_lshl_add_u64 v[8:9], v[8:9], 2, s[40:41]
	v_lshl_add_u64 v[10:11], v[10:11], 2, s[40:41]
	v_lshl_add_u64 v[0:1], v[0:1], 0, s[10:11]
	v_lshl_add_u64 v[2:3], v[2:3], 0, s[10:11]
	v_lshl_add_u64 v[8:9], v[8:9], 0, s[10:11]
	v_lshl_add_u64 v[10:11], v[10:11], 0, s[10:11]
	v_lshl_add_u64 v[0:1], v[0:1], 0, v[168:169]
	v_lshl_add_u64 v[4:5], v[2:3], 0, v[168:169]
	v_lshl_add_u64 v[8:9], v[8:9], 0, v[168:169]
	s_waitcnt vmcnt(12)
	v_lshl_add_u64 v[12:13], v[10:11], 0, v[168:169]
	global_load_dwordx4 v[0:3], v[0:1], off nt
	s_nop 0
	global_load_dwordx4 v[4:7], v[4:5], off nt
	s_nop 0
	global_load_dwordx4 v[8:11], v[8:9], off nt
	s_nop 0
	global_load_dwordx4 v[12:15], v[12:13], off nt
	s_add_u32 s48, s58, s7
	s_addc_u32 s49, s59, 0
	s_add_u32 s58, s66, s8
	s_addc_u32 s59, s67, 0
	s_branch .LBB0_85

.LBB0_93:
	s_waitcnt vmcnt(11)
	v_mov_b32_e32 v32, v200
	s_andn2_b64 vcc, exec, s[78:79]
	v_lshlrev_b32_e32 v34, 2, v32
	v_ashrrev_i32_e32 v33, 5, v32
	v_and_b32_e32 v34, 0x7c, v34
	v_mul_u32_u24_e32 v34, 0x104, v34
	v_lshlrev_b32_e32 v33, 2, v33
	v_add3_u32 v33, 0, v34, v33
	v_cndmask_b32_e64 v34, 0, 1, s[78:79]
	v_cmp_ne_u32_e64 s[40:41], 1, v34
	s_barrier
	s_waitcnt vmcnt(2)
	ds_write2_b32 v33, v0, v4 offset1:16
	ds_write2_b32 v33, v1, v5 offset0:65 offset1:81
	ds_write2_b32 v33, v2, v6 offset0:130 offset1:146
	ds_write2_b32 v33, v3, v7 offset0:195 offset1:211
	s_waitcnt vmcnt(0)
	ds_write2_b32 v33, v8, v12 offset0:32 offset1:48
	ds_write2_b32 v33, v9, v13 offset0:97 offset1:113
	ds_write2_b32 v33, v10, v14 offset0:162 offset1:178
	ds_write2_b32 v33, v11, v15 offset0:227 offset1:243
	s_cbranch_vccnz .LBB0_95
	v_mov_b32_e32 v18, v200
	s_ashr_i32 s75, s74, 31
	v_ashrrev_i32_e32 v16, 5, v18
	v_add_u32_e32 v26, s72, v16
	v_lshlrev_b32_e32 v18, 4, v18
	v_mad_i64_i32 v[16:17], s[8:9], s38, v26, 0
	v_and_b32_e32 v168, 0x1f0, v18
	v_add_u32_e32 v18, 16, v26
	v_add_u32_e32 v24, 32, v26
	v_add_u32_e32 v26, 48, v26
	v_mad_i64_i32 v[18:19], s[10:11], s38, v18, 0
	v_mad_i64_i32 v[24:25], s[10:11], s38, v24, 0
	v_mad_i64_i32 v[26:27], s[10:11], s38, v26, 0
	v_lshl_add_u64 v[16:17], v[16:17], 2, s[76:77]
	s_lshl_b64 s[8:9], s[74:75], 2
	v_lshl_add_u64 v[18:19], v[18:19], 2, s[76:77]
	v_lshl_add_u64 v[24:25], v[24:25], 2, s[76:77]
	v_lshl_add_u64 v[26:27], v[26:27], 2, s[76:77]
	v_lshl_add_u64 v[16:17], v[16:17], 0, s[8:9]
	v_lshl_add_u64 v[18:19], v[18:19], 0, s[8:9]
	v_lshl_add_u64 v[24:25], v[24:25], 0, s[8:9]
	v_lshl_add_u64 v[26:27], v[26:27], 0, s[8:9]
	v_lshl_add_u64 v[16:17], v[16:17], 0, v[168:169]
	v_lshl_add_u64 v[18:19], v[18:19], 0, v[168:169]
	v_lshl_add_u64 v[24:25], v[24:25], 0, v[168:169]
	v_lshl_add_u64 v[26:27], v[26:27], 0, v[168:169]
	global_load_dwordx4 v[20:23], v[16:17], off nt
	s_nop 0
	global_load_dwordx4 v[16:19], v[18:19], off nt
	s_nop 0
	global_load_dwordx4 v[28:31], v[24:25], off nt
	s_nop 0
	global_load_dwordx4 v[24:27], v[26:27], off nt

.LBB0_104:
	v_mov_b32_e32 v32, v200
	s_andn2_b64 vcc, exec, s[76:77]
	v_lshlrev_b32_e32 v34, 2, v32
	v_ashrrev_i32_e32 v33, 5, v32
	v_and_b32_e32 v34, 0x7c, v34
	v_mul_u32_u24_e32 v34, 0x104, v34
	v_lshlrev_b32_e32 v33, 2, v33
	v_add3_u32 v33, 0, v34, v33
	s_barrier
	s_waitcnt vmcnt(4)
	ds_write2_b32 v33, v20, v16 offset1:16
	ds_write2_b32 v33, v21, v17 offset0:65 offset1:81
	ds_write2_b32 v33, v22, v18 offset0:130 offset1:146
	ds_write2_b32 v33, v23, v19 offset0:195 offset1:211
	s_waitcnt vmcnt(2)
	ds_write2_b32 v33, v28, v24 offset0:32 offset1:48
	ds_write2_b32 v33, v29, v25 offset0:97 offset1:113
	ds_write2_b32 v33, v30, v26 offset0:162 offset1:178
	ds_write2_b32 v33, v31, v27 offset0:227 offset1:243
	s_cbranch_vccnz .LBB0_83
	v_mov_b32_e32 v2, v200
	s_ashr_i32 s61, s60, 31
	v_ashrrev_i32_e32 v0, 5, v2
	v_add_u32_e32 v10, s42, v0
	v_lshlrev_b32_e32 v2, 4, v2
	v_mad_i64_i32 v[0:1], s[8:9], s38, v10, 0
	v_and_b32_e32 v168, 0x1f0, v2
	v_add_u32_e32 v2, 16, v10
	v_add_u32_e32 v8, 32, v10
	v_add_u32_e32 v10, 48, v10
	v_mad_i64_i32 v[2:3], s[10:11], s38, v2, 0
	v_mad_i64_i32 v[8:9], s[10:11], s38, v8, 0
	v_mad_i64_i32 v[10:11], s[10:11], s38, v10, 0
	v_lshl_add_u64 v[0:1], v[0:1], 2, s[40:41]
	s_lshl_b64 s[8:9], s[60:61], 2
	v_lshl_add_u64 v[2:3], v[2:3], 2, s[40:41]
	v_lshl_add_u64 v[8:9], v[8:9], 2, s[40:41]
	v_lshl_add_u64 v[10:11], v[10:11], 2, s[40:41]
	v_lshl_add_u64 v[0:1], v[0:1], 0, s[8:9]
	v_lshl_add_u64 v[2:3], v[2:3], 0, s[8:9]
	v_lshl_add_u64 v[8:9], v[8:9], 0, s[8:9]
	v_lshl_add_u64 v[10:11], v[10:11], 0, s[8:9]
	v_lshl_add_u64 v[0:1], v[0:1], 0, v[168:169]
	v_lshl_add_u64 v[4:5], v[2:3], 0, v[168:169]
	v_lshl_add_u64 v[8:9], v[8:9], 0, v[168:169]
	v_lshl_add_u64 v[12:13], v[10:11], 0, v[168:169]
	global_load_dwordx4 v[0:3], v[0:1], off nt
	s_nop 0
	global_load_dwordx4 v[4:7], v[4:5], off nt
	s_nop 0
	global_load_dwordx4 v[8:11], v[8:9], off nt
	s_nop 0
	global_load_dwordx4 v[12:15], v[12:13], off nt
	s_branch .LBB0_83

.LBB0_109:
	v_ashrrev_i32_e32 v3, 16, v2
	s_waitcnt vmcnt(4)
	v_and_or_b32 v4, v3, -2, s0
	v_ashrrev_i32_e32 v5, 31, v4
	v_and_b32_e32 v1, 0x3fc, v0
	v_lshlrev_b64 v[4:5], 19, v[4:5]
	v_and_b32_e32 v3, 0x7fc00, v0
	v_or3_b32 v4, v4, v3, v1
	s_waitcnt vmcnt(3)
	v_lshlrev_b64 v[8:9], 2, v[4:5]
	v_lshl_add_u64 v[4:5], s[44:45], 0, v[8:9]
	v_lshl_add_u64 v[8:9], s[46:47], 0, v[8:9]
	global_load_dwordx4 v[4:7], v[4:5], off nt
	v_ashrrev_i32_e32 v1, 31, v0
	global_load_dwordx4 v[8:11], v[8:9], off nt
	s_waitcnt vmcnt(1)
	v_cvt_pk_bf16_f32 v4, v4, v5
	v_cvt_pk_bf16_f32 v5, v6, v7
	s_waitcnt vmcnt(0)
	v_cvt_pk_bf16_f32 v6, v8, v9
	v_lshlrev_b64 v[8:9], 1, v[0:1]
	v_add_u32_e32 v2, s6, v2
	s_mov_b32 s1, 0x3ffff
	v_cvt_pk_bf16_f32 v7, v10, v11
	v_lshl_add_u64 v[10:11], s[20:21], 0, v[8:9]
	v_cmp_lt_i32_e32 vcc, s1, v2
	global_store_dwordx2 v[10:11], v[4:5], off
	v_lshl_add_u64 v[4:5], s[24:25], 0, v[8:9]
	v_add_u32_e32 v0, s8, v0
	s_or_b64 s[40:41], vcc, s[40:41]
	global_store_dwordx2 v[4:5], v[6:7], off
	s_andn2_b64 exec, exec, s[40:41]
	s_cbranch_execnz .LBB0_109

.LBB0_178:
	s_or_b64 exec, exec, s[18:19]
	s_ashr_i32 s7, s38, 7
	v_lshlrev_b32_e32 v139, 10, v138
	v_mov_b64_e32 v[140:141], s[48:49]
	s_and_b32 s8, s7, -2
	v_and_b32_e32 v151, 0x33c00, v139
	v_mad_i64_i32 v[138:139], s[12:13], v138, s82, v[140:141]
	s_ashr_i32 s65, s64, 31
	s_add_i32 s7, s10, 0xfffff400
	v_lshl_add_u64 v[138:139], s[64:65], 1, v[138:139]
	s_cmp_lt_u32 s7, 0xfffff800
	v_lshl_add_u64 v[142:143], v[138:139], 0, v[168:169]
	v_cvt_pk_bf16_f32 v138, v124, v125
	v_cvt_pk_bf16_f32 v139, v126, v127
	v_cvt_pk_bf16_f32 v140, v120, v121
	s_cselect_b64 s[74:75], -1, 0
	v_cvt_pk_bf16_f32 v141, v122, v123
	global_store_dwordx2 v[142:143], v[138:139], off
	global_store_dwordx2 v[142:143], v[140:141], off offset:32
	s_nor_b64 s[12:13], s[74:75], vcc
	v_lshlrev_b32_e32 v138, 2, v132
	v_lshlrev_b32_e32 v140, 2, v151
	s_and_saveexec_b64 s[18:19], s[12:13]
	s_cbranch_execz .LBB0_180
	s_and_b64 s[12:13], s[66:67], exec
	s_cselect_b32 s7, s23, 0xc000000
	s_add_u32 s7, s44, s7
	s_addc_u32 s11, s45, 0
	s_or_b32 s12, s8, s0
	s_ashr_i32 s13, s12, 31
	s_lshl_b64 s[12:13], s[12:13], 20
	s_add_u32 s12, s7, s12
	s_addc_u32 s13, s11, s13
	v_mov_b32_e32 v141, v169
	s_and_b32 s7, s64, 0x360
	v_lshl_add_u64 v[152:153], s[12:13], 0, v[140:141]
	s_lshl_b32 s70, s7, 2
	v_lshl_add_u64 v[152:153], v[152:153], 0, s[70:71]
	v_mov_b32_e32 v139, v169
	v_lshl_add_u64 v[152:153], v[152:153], 0, v[138:139]
	global_store_dwordx4 v[152:153], v[124:127], off nt
	global_store_dwordx4 v[152:153], v[120:123], off offset:64 nt

.LBB0_182:
	s_or_b64 exec, exec, s[18:19]
	s_addk_i32 s10, 0xf480
	s_cmp_lt_u32 s10, 0xfffff800
	s_cselect_b64 s[76:77], -1, 0
	v_cvt_pk_bf16_f32 v120, v116, v117
	v_cvt_pk_bf16_f32 v121, v118, v119
	s_nor_b64 s[10:11], s[76:77], vcc
	v_cvt_pk_bf16_f32 v122, v112, v113
	v_cvt_pk_bf16_f32 v123, v114, v115
	global_store_dwordx2 v[142:143], v[120:121], off offset:256
	global_store_dwordx2 v[142:143], v[122:123], off offset:288
	s_and_saveexec_b64 s[18:19], s[10:11]
	s_cbranch_execz .LBB0_184
	s_and_b64 s[10:11], s[72:73], exec
	s_cselect_b32 s10, s23, 0xc000000
	s_add_u32 s12, s44, s10
	s_addc_u32 s13, s45, 0
	s_or_b32 s10, s8, s0
	s_ashr_i32 s11, s10, 31
	s_lshl_b64 s[10:11], s[10:11], 20
	s_add_u32 s10, s12, s10
	s_addc_u32 s11, s13, s11
	v_mov_b32_e32 v141, v169
	v_lshl_add_u64 v[120:121], s[10:11], 0, v[140:141]
	s_and_b32 s10, s7, 0x3e0
	s_lshl_b32 s70, s10, 2
	v_lshl_add_u64 v[120:121], v[120:121], 0, s[70:71]
	v_mov_b32_e32 v139, v169
	v_lshl_add_u64 v[120:121], v[120:121], 0, v[138:139]
	global_store_dwordx4 v[120:121], v[116:119], off nt
	global_store_dwordx4 v[120:121], v[112:115], off offset:64 nt

.LBB0_186:
	s_or_b64 exec, exec, s[18:19]
	v_lshlrev_b32_e32 v115, 10, v114
	v_mov_b64_e32 v[116:117], s[48:49]
	v_and_b32_e32 v120, 0x37c00, v115
	v_mad_i64_i32 v[114:115], s[10:11], v114, s82, v[116:117]
	v_lshl_add_u64 v[114:115], s[64:65], 1, v[114:115]
	v_lshl_add_u64 v[116:117], v[114:115], 0, v[168:169]
	v_cvt_pk_bf16_f32 v114, v108, v109
	v_cvt_pk_bf16_f32 v115, v110, v111
	v_cvt_pk_bf16_f32 v118, v104, v105
	v_cvt_pk_bf16_f32 v119, v106, v107
	global_store_dwordx2 v[116:117], v[114:115], off
	global_store_dwordx2 v[116:117], v[118:119], off offset:32
	s_nor_b64 s[10:11], s[74:75], vcc
	v_lshlrev_b32_e32 v114, 2, v120
	s_and_saveexec_b64 s[18:19], s[10:11]
	s_cbranch_execz .LBB0_188
	s_and_b64 s[10:11], s[66:67], exec
	s_cselect_b32 s10, s23, 0xc000000
	s_add_u32 s12, s44, s10
	s_addc_u32 s13, s45, 0
	s_or_b32 s10, s8, s0
	s_ashr_i32 s11, s10, 31
	s_lshl_b64 s[10:11], s[10:11], 20
	s_add_u32 s10, s12, s10
	s_addc_u32 s11, s13, s11
	v_mov_b32_e32 v115, v169
	v_lshl_add_u64 v[118:119], s[10:11], 0, v[114:115]
	s_and_b32 s10, s64, 0x360
	s_lshl_b32 s70, s10, 2
	v_lshl_add_u64 v[118:119], v[118:119], 0, s[70:71]
	v_mov_b32_e32 v139, v169
	v_lshl_add_u64 v[118:119], v[118:119], 0, v[138:139]
	global_store_dwordx4 v[118:119], v[108:111], off nt
	global_store_dwordx4 v[118:119], v[104:107], off offset:64 nt

.LBB0_190:
	s_or_b64 exec, exec, s[18:19]
	v_cvt_pk_bf16_f32 v104, v100, v101
	v_cvt_pk_bf16_f32 v105, v102, v103
	s_nor_b64 s[10:11], s[76:77], vcc
	v_cvt_pk_bf16_f32 v106, v96, v97
	v_cvt_pk_bf16_f32 v107, v98, v99
	global_store_dwordx2 v[116:117], v[104:105], off offset:256
	global_store_dwordx2 v[116:117], v[106:107], off offset:288
	s_and_saveexec_b64 s[18:19], s[10:11]
	s_cbranch_execz .LBB0_192
	s_and_b64 s[10:11], s[72:73], exec
	s_cselect_b32 s10, s23, 0xc000000
	s_add_u32 s12, s44, s10
	s_addc_u32 s13, s45, 0
	s_or_b32 s10, s8, s0
	s_ashr_i32 s11, s10, 31
	s_lshl_b64 s[10:11], s[10:11], 20
	s_add_u32 s10, s12, s10
	s_addc_u32 s11, s13, s11
	v_mov_b32_e32 v115, v169
	v_lshl_add_u64 v[104:105], s[10:11], 0, v[114:115]
	s_and_b32 s10, s7, 0x3e0
	s_lshl_b32 s70, s10, 2
	v_lshl_add_u64 v[104:105], v[104:105], 0, s[70:71]
	v_mov_b32_e32 v139, v169
	v_lshl_add_u64 v[104:105], v[104:105], 0, v[138:139]
	global_store_dwordx4 v[104:105], v[100:103], off nt
	global_store_dwordx4 v[104:105], v[96:99], off offset:64 nt

.LBB0_194:
	s_or_b64 exec, exec, s[18:19]
	v_lshlrev_b32_e32 v99, 10, v98
	v_mov_b64_e32 v[100:101], s[48:49]
	v_and_b32_e32 v104, 0x3bc00, v99
	v_mad_i64_i32 v[98:99], s[10:11], v98, s82, v[100:101]
	v_lshl_add_u64 v[98:99], s[64:65], 1, v[98:99]
	v_lshl_add_u64 v[100:101], v[98:99], 0, v[168:169]
	v_cvt_pk_bf16_f32 v98, v92, v93
	v_cvt_pk_bf16_f32 v99, v94, v95
	v_cvt_pk_bf16_f32 v102, v88, v89
	v_cvt_pk_bf16_f32 v103, v90, v91
	global_store_dwordx2 v[100:101], v[98:99], off
	global_store_dwordx2 v[100:101], v[102:103], off offset:32
	s_nor_b64 s[10:11], s[74:75], vcc
	v_lshlrev_b32_e32 v98, 2, v104
	s_and_saveexec_b64 s[18:19], s[10:11]
	s_cbranch_execz .LBB0_196
	s_and_b64 s[10:11], s[66:67], exec
	s_cselect_b32 s10, s23, 0xc000000
	s_add_u32 s12, s44, s10
	s_addc_u32 s13, s45, 0
	s_or_b32 s10, s8, s0
	s_ashr_i32 s11, s10, 31
	s_lshl_b64 s[10:11], s[10:11], 20
	s_add_u32 s10, s12, s10
	s_addc_u32 s11, s13, s11
	v_mov_b32_e32 v99, v169
	v_lshl_add_u64 v[102:103], s[10:11], 0, v[98:99]
	s_and_b32 s10, s64, 0x360
	s_lshl_b32 s70, s10, 2
	v_lshl_add_u64 v[102:103], v[102:103], 0, s[70:71]
	v_mov_b32_e32 v139, v169
	v_lshl_add_u64 v[102:103], v[102:103], 0, v[138:139]
	global_store_dwordx4 v[102:103], v[92:95], off nt
	global_store_dwordx4 v[102:103], v[88:91], off offset:64 nt

.LBB0_198:
	s_or_b64 exec, exec, s[18:19]
	v_cvt_pk_bf16_f32 v88, v84, v85
	v_cvt_pk_bf16_f32 v89, v86, v87
	s_nor_b64 s[10:11], s[76:77], vcc
	v_cvt_pk_bf16_f32 v90, v80, v81
	v_cvt_pk_bf16_f32 v91, v82, v83
	global_store_dwordx2 v[100:101], v[88:89], off offset:256
	global_store_dwordx2 v[100:101], v[90:91], off offset:288
	s_and_saveexec_b64 s[18:19], s[10:11]
	s_cbranch_execz .LBB0_200
	s_and_b64 s[10:11], s[72:73], exec
	s_cselect_b32 s10, s23, 0xc000000
	s_add_u32 s12, s44, s10
	s_addc_u32 s13, s45, 0
	s_or_b32 s10, s8, s0
	s_ashr_i32 s11, s10, 31
	s_lshl_b64 s[10:11], s[10:11], 20
	s_add_u32 s10, s12, s10
	s_addc_u32 s11, s13, s11
	v_mov_b32_e32 v99, v169
	v_lshl_add_u64 v[88:89], s[10:11], 0, v[98:99]
	s_and_b32 s10, s7, 0x3e0
	s_lshl_b32 s70, s10, 2
	v_lshl_add_u64 v[88:89], v[88:89], 0, s[70:71]
	v_mov_b32_e32 v139, v169
	v_lshl_add_u64 v[88:89], v[88:89], 0, v[138:139]
	global_store_dwordx4 v[88:89], v[84:87], off nt
	global_store_dwordx4 v[88:89], v[80:83], off offset:64 nt

.LBB0_202:
	s_or_b64 exec, exec, s[18:19]
	v_lshlrev_b32_e32 v83, 10, v82
	v_mov_b64_e32 v[84:85], s[48:49]
	v_and_b32_e32 v88, 0x3fc00, v83
	v_mad_i64_i32 v[82:83], s[10:11], v82, s82, v[84:85]
	v_lshl_add_u64 v[82:83], s[64:65], 1, v[82:83]
	v_lshl_add_u64 v[84:85], v[82:83], 0, v[168:169]
	v_cvt_pk_bf16_f32 v82, v76, v77
	v_cvt_pk_bf16_f32 v83, v78, v79
	v_cvt_pk_bf16_f32 v86, v72, v73
	v_cvt_pk_bf16_f32 v87, v74, v75
	global_store_dwordx2 v[84:85], v[82:83], off
	global_store_dwordx2 v[84:85], v[86:87], off offset:32
	s_nor_b64 s[10:11], s[74:75], vcc
	v_lshlrev_b32_e32 v82, 2, v88
	s_and_saveexec_b64 s[18:19], s[10:11]
	s_cbranch_execz .LBB0_204
	s_and_b64 s[10:11], s[66:67], exec
	s_cselect_b32 s9, s23, 0xc000000
	s_add_u32 s9, s44, s9
	s_addc_u32 s12, s45, 0
	s_or_b32 s10, s8, s0
	s_ashr_i32 s11, s10, 31
	s_lshl_b64 s[10:11], s[10:11], 20
	s_add_u32 s10, s9, s10
	s_addc_u32 s11, s12, s11
	v_mov_b32_e32 v83, v169
	s_and_b32 s9, s64, 0x360
	v_lshl_add_u64 v[86:87], s[10:11], 0, v[82:83]
	s_lshl_b32 s70, s9, 2
	v_lshl_add_u64 v[86:87], v[86:87], 0, s[70:71]
	v_mov_b32_e32 v139, v169
	v_lshl_add_u64 v[86:87], v[86:87], 0, v[138:139]
	global_store_dwordx4 v[86:87], v[76:79], off nt
	global_store_dwordx4 v[86:87], v[72:75], off offset:64 nt

.LBB0_206:
	s_or_b64 exec, exec, s[18:19]
	v_cvt_pk_bf16_f32 v72, v68, v69
	v_cvt_pk_bf16_f32 v73, v70, v71
	s_nor_b64 s[10:11], s[76:77], vcc
	v_cvt_pk_bf16_f32 v74, v64, v65
	v_cvt_pk_bf16_f32 v75, v66, v67
	global_store_dwordx2 v[84:85], v[72:73], off offset:256
	global_store_dwordx2 v[84:85], v[74:75], off offset:288
	s_and_saveexec_b64 s[18:19], s[10:11]
	s_cbranch_execz .LBB0_208
	s_and_b64 s[10:11], s[72:73], exec
	s_cselect_b32 s9, s23, 0xc000000
	s_add_u32 s10, s44, s9
	s_addc_u32 s11, s45, 0
	s_or_b32 s8, s8, s0
	s_ashr_i32 s9, s8, 31
	s_lshl_b64 s[8:9], s[8:9], 20
	s_add_u32 s8, s10, s8
	s_addc_u32 s9, s11, s9
	v_mov_b32_e32 v83, v169
	v_lshl_add_u64 v[72:73], s[8:9], 0, v[82:83]
	s_and_b32 s8, s7, 0x3e0
	s_lshl_b32 s70, s8, 2
	v_lshl_add_u64 v[72:73], v[72:73], 0, s[70:71]
	v_mov_b32_e32 v139, v169
	v_lshl_add_u64 v[72:73], v[72:73], 0, v[138:139]
	global_store_dwordx4 v[72:73], v[68:71], off nt
	global_store_dwordx4 v[72:73], v[64:67], off offset:64 nt

.LBB0_210:
	s_or_b64 exec, exec, s[18:19]
	v_lshlrev_b32_e32 v67, 10, v66
	v_mov_b64_e32 v[68:69], s[48:49]
	v_and_b32_e32 v72, 0x33c00, v67
	v_mad_i64_i32 v[66:67], s[10:11], v66, s82, v[68:69]
	v_lshl_add_u64 v[66:67], s[64:65], 1, v[66:67]
	s_ashr_i32 s8, s38, 7
	v_lshl_add_u64 v[68:69], v[66:67], 0, v[168:169]
	v_cvt_pk_bf16_f32 v66, v60, v61
	v_cvt_pk_bf16_f32 v67, v62, v63
	s_and_b32 s8, s8, -2
	v_cvt_pk_bf16_f32 v70, v56, v57
	v_cvt_pk_bf16_f32 v71, v58, v59
	global_store_dwordx2 v[68:69], v[66:67], off
	global_store_dwordx2 v[68:69], v[70:71], off offset:32
	s_nor_b64 s[10:11], s[74:75], vcc
	v_lshlrev_b32_e32 v66, 2, v72
	s_and_saveexec_b64 s[18:19], s[10:11]
	s_cbranch_execz .LBB0_212
	s_and_b64 s[10:11], s[66:67], exec
	s_cselect_b32 s10, s23, 0xc000000
	s_add_u32 s12, s44, s10
	s_addc_u32 s13, s45, 0
	s_or_b32 s10, s8, s0
	s_ashr_i32 s11, s10, 31
	s_lshl_b64 s[10:11], s[10:11], 20
	s_add_u32 s10, s12, s10
	s_addc_u32 s11, s13, s11
	v_mov_b32_e32 v67, v169
	v_lshl_add_u64 v[70:71], s[10:11], 0, v[66:67]
	s_and_b32 s10, s64, 0x360
	s_lshl_b32 s70, s10, 2
	v_lshl_add_u64 v[70:71], v[70:71], 0, s[70:71]
	v_mov_b32_e32 v139, v169
	v_lshl_add_u64 v[70:71], v[70:71], 0, v[138:139]
	global_store_dwordx4 v[70:71], v[60:63], off nt
	global_store_dwordx4 v[70:71], v[56:59], off offset:64 nt

.LBB0_214:
	s_or_b64 exec, exec, s[18:19]
	v_cvt_pk_bf16_f32 v56, v52, v53
	v_cvt_pk_bf16_f32 v57, v54, v55
	s_nor_b64 s[10:11], s[76:77], vcc
	v_cvt_pk_bf16_f32 v58, v48, v49
	v_cvt_pk_bf16_f32 v59, v50, v51
	global_store_dwordx2 v[68:69], v[56:57], off offset:256
	global_store_dwordx2 v[68:69], v[58:59], off offset:288
	s_and_saveexec_b64 s[18:19], s[10:11]
	s_cbranch_execz .LBB0_216
	s_and_b64 s[10:11], s[72:73], exec
	s_cselect_b32 s10, s23, 0xc000000
	s_add_u32 s12, s44, s10
	s_addc_u32 s13, s45, 0
	s_or_b32 s10, s8, s0
	s_ashr_i32 s11, s10, 31
	s_lshl_b64 s[10:11], s[10:11], 20
	s_add_u32 s10, s12, s10
	s_addc_u32 s11, s13, s11
	v_mov_b32_e32 v67, v169
	v_lshl_add_u64 v[56:57], s[10:11], 0, v[66:67]
	s_and_b32 s10, s7, 0x3e0
	s_lshl_b32 s70, s10, 2
	v_lshl_add_u64 v[56:57], v[56:57], 0, s[70:71]
	v_mov_b32_e32 v139, v169
	v_lshl_add_u64 v[56:57], v[56:57], 0, v[138:139]
	global_store_dwordx4 v[56:57], v[52:55], off nt
	global_store_dwordx4 v[56:57], v[48:51], off offset:64 nt

.LBB0_218:
	s_or_b64 exec, exec, s[18:19]
	v_lshlrev_b32_e32 v51, 10, v50
	v_mov_b64_e32 v[52:53], s[48:49]
	v_and_b32_e32 v56, 0x37c00, v51
	v_mad_i64_i32 v[50:51], s[10:11], v50, s82, v[52:53]
	v_lshl_add_u64 v[50:51], s[64:65], 1, v[50:51]
	v_lshl_add_u64 v[52:53], v[50:51], 0, v[168:169]
	v_cvt_pk_bf16_f32 v50, v44, v45
	v_cvt_pk_bf16_f32 v51, v46, v47
	v_cvt_pk_bf16_f32 v54, v40, v41
	v_cvt_pk_bf16_f32 v55, v42, v43
	global_store_dwordx2 v[52:53], v[50:51], off
	global_store_dwordx2 v[52:53], v[54:55], off offset:32
	s_nor_b64 s[10:11], s[74:75], vcc
	v_lshlrev_b32_e32 v50, 2, v56
	s_and_saveexec_b64 s[18:19], s[10:11]
	s_cbranch_execz .LBB0_220
	s_and_b64 s[10:11], s[66:67], exec
	s_cselect_b32 s10, s23, 0xc000000
	s_add_u32 s12, s44, s10
	s_addc_u32 s13, s45, 0
	s_or_b32 s10, s8, s0
	s_ashr_i32 s11, s10, 31
	s_lshl_b64 s[10:11], s[10:11], 20
	s_add_u32 s10, s12, s10
	s_addc_u32 s11, s13, s11
	v_mov_b32_e32 v51, v169
	v_lshl_add_u64 v[54:55], s[10:11], 0, v[50:51]
	s_and_b32 s10, s64, 0x360
	s_lshl_b32 s70, s10, 2
	v_lshl_add_u64 v[54:55], v[54:55], 0, s[70:71]
	v_mov_b32_e32 v139, v169
	v_lshl_add_u64 v[54:55], v[54:55], 0, v[138:139]
	global_store_dwordx4 v[54:55], v[44:47], off nt
	global_store_dwordx4 v[54:55], v[40:43], off offset:64 nt

.LBB0_222:
	s_or_b64 exec, exec, s[18:19]
	v_cvt_pk_bf16_f32 v40, v36, v37
	v_cvt_pk_bf16_f32 v41, v38, v39
	s_nor_b64 s[10:11], s[76:77], vcc
	v_cvt_pk_bf16_f32 v42, v32, v33
	v_cvt_pk_bf16_f32 v43, v34, v35
	global_store_dwordx2 v[52:53], v[40:41], off offset:256
	global_store_dwordx2 v[52:53], v[42:43], off offset:288
	s_and_saveexec_b64 s[18:19], s[10:11]
	s_cbranch_execz .LBB0_224
	s_and_b64 s[10:11], s[72:73], exec
	s_cselect_b32 s10, s23, 0xc000000
	s_add_u32 s12, s44, s10
	s_addc_u32 s13, s45, 0
	s_or_b32 s10, s8, s0
	s_ashr_i32 s11, s10, 31
	s_lshl_b64 s[10:11], s[10:11], 20
	s_add_u32 s10, s12, s10
	s_addc_u32 s11, s13, s11
	v_mov_b32_e32 v51, v169
	v_lshl_add_u64 v[40:41], s[10:11], 0, v[50:51]
	s_and_b32 s10, s7, 0x3e0
	s_lshl_b32 s70, s10, 2
	v_lshl_add_u64 v[40:41], v[40:41], 0, s[70:71]
	v_mov_b32_e32 v139, v169
	v_lshl_add_u64 v[40:41], v[40:41], 0, v[138:139]
	global_store_dwordx4 v[40:41], v[36:39], off nt
	global_store_dwordx4 v[40:41], v[32:35], off offset:64 nt

.LBB0_226:
	s_or_b64 exec, exec, s[18:19]
	v_lshlrev_b32_e32 v35, 10, v34
	v_mov_b64_e32 v[36:37], s[48:49]
	v_and_b32_e32 v40, 0x3bc00, v35
	v_mad_i64_i32 v[34:35], s[10:11], v34, s82, v[36:37]
	v_lshl_add_u64 v[34:35], s[64:65], 1, v[34:35]
	v_lshl_add_u64 v[36:37], v[34:35], 0, v[168:169]
	v_cvt_pk_bf16_f32 v34, v28, v29
	v_cvt_pk_bf16_f32 v35, v30, v31
	v_cvt_pk_bf16_f32 v38, v24, v25
	v_cvt_pk_bf16_f32 v39, v26, v27
	global_store_dwordx2 v[36:37], v[34:35], off
	global_store_dwordx2 v[36:37], v[38:39], off offset:32
	s_nor_b64 s[10:11], s[74:75], vcc
	v_lshlrev_b32_e32 v34, 2, v40
	s_and_saveexec_b64 s[18:19], s[10:11]
	s_cbranch_execz .LBB0_228
	s_and_b64 s[10:11], s[66:67], exec
	s_cselect_b32 s10, s23, 0xc000000
	s_add_u32 s12, s44, s10
	s_addc_u32 s13, s45, 0
	s_or_b32 s10, s8, s0
	s_ashr_i32 s11, s10, 31
	s_lshl_b64 s[10:11], s[10:11], 20
	s_add_u32 s10, s12, s10
	s_addc_u32 s11, s13, s11
	v_mov_b32_e32 v35, v169
	v_lshl_add_u64 v[38:39], s[10:11], 0, v[34:35]
	s_and_b32 s10, s64, 0x360
	s_lshl_b32 s70, s10, 2
	v_lshl_add_u64 v[38:39], v[38:39], 0, s[70:71]
	v_mov_b32_e32 v139, v169
	v_lshl_add_u64 v[38:39], v[38:39], 0, v[138:139]
	global_store_dwordx4 v[38:39], v[28:31], off nt
	global_store_dwordx4 v[38:39], v[24:27], off offset:64 nt

.LBB0_230:
	s_or_b64 exec, exec, s[18:19]
	v_cvt_pk_bf16_f32 v24, v20, v21
	v_cvt_pk_bf16_f32 v25, v22, v23
	s_nor_b64 s[10:11], s[76:77], vcc
	v_cvt_pk_bf16_f32 v26, v16, v17
	v_cvt_pk_bf16_f32 v27, v18, v19
	global_store_dwordx2 v[36:37], v[24:25], off offset:256
	global_store_dwordx2 v[36:37], v[26:27], off offset:288
	s_and_saveexec_b64 s[18:19], s[10:11]
	s_cbranch_execz .LBB0_232
	s_and_b64 s[10:11], s[72:73], exec
	s_cselect_b32 s10, s23, 0xc000000
	s_add_u32 s12, s44, s10
	s_addc_u32 s13, s45, 0
	s_or_b32 s10, s8, s0
	s_ashr_i32 s11, s10, 31
	s_lshl_b64 s[10:11], s[10:11], 20
	s_add_u32 s10, s12, s10
	s_addc_u32 s11, s13, s11
	v_mov_b32_e32 v35, v169
	v_lshl_add_u64 v[24:25], s[10:11], 0, v[34:35]
	s_and_b32 s10, s7, 0x3e0
	s_lshl_b32 s70, s10, 2
	v_lshl_add_u64 v[24:25], v[24:25], 0, s[70:71]
	v_mov_b32_e32 v139, v169
	v_lshl_add_u64 v[24:25], v[24:25], 0, v[138:139]
	global_store_dwordx4 v[24:25], v[20:23], off nt
	global_store_dwordx4 v[24:25], v[16:19], off offset:64 nt

.LBB0_234:
	s_or_b64 exec, exec, s[18:19]
	v_lshlrev_b32_e32 v19, 10, v18
	v_mov_b64_e32 v[20:21], s[48:49]
	v_and_b32_e32 v24, 0x3fc00, v19
	v_mad_i64_i32 v[18:19], s[10:11], v18, s82, v[20:21]
	v_lshl_add_u64 v[18:19], s[64:65], 1, v[18:19]
	v_lshl_add_u64 v[20:21], v[18:19], 0, v[168:169]
	v_cvt_pk_bf16_f32 v18, v12, v13
	v_cvt_pk_bf16_f32 v19, v14, v15
	v_cvt_pk_bf16_f32 v22, v8, v9
	v_cvt_pk_bf16_f32 v23, v10, v11
	global_store_dwordx2 v[20:21], v[18:19], off
	global_store_dwordx2 v[20:21], v[22:23], off offset:32
	s_nor_b64 s[10:11], s[74:75], vcc
	v_lshlrev_b32_e32 v18, 2, v24
	s_and_saveexec_b64 s[18:19], s[10:11]
	s_cbranch_execz .LBB0_236
	s_and_b64 s[10:11], s[66:67], exec
	s_cselect_b32 s9, s23, 0xc000000
	s_add_u32 s9, s44, s9
	s_addc_u32 s12, s45, 0
	s_or_b32 s10, s8, s0
	s_ashr_i32 s11, s10, 31
	s_lshl_b64 s[10:11], s[10:11], 20
	s_add_u32 s10, s9, s10
	s_addc_u32 s11, s12, s11
	v_mov_b32_e32 v19, v169
	s_and_b32 s9, s64, 0x360
	v_lshl_add_u64 v[22:23], s[10:11], 0, v[18:19]
	s_lshl_b32 s70, s9, 2
	v_lshl_add_u64 v[22:23], v[22:23], 0, s[70:71]
	v_mov_b32_e32 v139, v169
	v_lshl_add_u64 v[22:23], v[22:23], 0, v[138:139]
	global_store_dwordx4 v[22:23], v[12:15], off nt
	global_store_dwordx4 v[22:23], v[8:11], off offset:64 nt

.LBB0_238:
	s_or_b64 exec, exec, s[18:19]
	v_cvt_pk_bf16_f32 v8, v4, v5
	v_cvt_pk_bf16_f32 v9, v6, v7
	s_nor_b64 s[10:11], s[76:77], vcc
	v_cvt_pk_bf16_f32 v10, v0, v1
	v_cvt_pk_bf16_f32 v11, v2, v3
	global_store_dwordx2 v[20:21], v[8:9], off offset:256
	global_store_dwordx2 v[20:21], v[10:11], off offset:288
	s_and_saveexec_b64 s[18:19], s[10:11]
	s_cbranch_execz .LBB0_240
	s_and_b64 s[10:11], s[72:73], exec
	s_cselect_b32 s9, s23, 0xc000000
	s_add_u32 s10, s44, s9
	s_addc_u32 s11, s45, 0
	s_or_b32 s8, s8, s0
	s_ashr_i32 s9, s8, 31
	s_lshl_b64 s[8:9], s[8:9], 20
	s_add_u32 s8, s10, s8
	s_addc_u32 s9, s11, s9
	v_mov_b32_e32 v19, v169
	s_and_b32 s7, s7, 0x3e0
	v_lshl_add_u64 v[8:9], s[8:9], 0, v[18:19]
	s_lshl_b32 s70, s7, 2
	v_lshl_add_u64 v[8:9], v[8:9], 0, s[70:71]
	v_mov_b32_e32 v139, v169
	v_lshl_add_u64 v[8:9], v[8:9], 0, v[138:139]
	global_store_dwordx4 v[8:9], v[4:7], off nt
	global_store_dwordx4 v[8:9], v[0:3], off offset:64 nt

.LBB0_521:
	v_ashrrev_i32_e32 v73, 31, v72
	v_lshlrev_b64 v[64:65], 12, v[72:73]
	v_lshl_add_u64 v[64:65], s[38:39], 0, v[64:65]
	s_mov_b64 s[4:5], 0x4000000
	v_mov_b64_e32 v[66:67], s[24:25]
	v_lshl_add_u64 v[84:85], v[64:65], 0, s[4:5]
	v_mad_i64_i32 v[66:67], s[4:5], v72, s82, v[66:67]
	s_mov_b64 s[4:5], 0x3800
	s_nop 0
	v_lshl_add_u64 v[86:87], v[66:67], 0, s[4:5]
	s_mov_b64 s[4:5], 0x4800
	v_lshl_add_u64 v[88:89], v[66:67], 0, s[28:29]
	v_lshl_add_u64 v[90:91], v[66:67], 0, s[4:5]
	s_mov_b64 s[4:5], 0x5000
	v_lshl_add_u64 v[102:103], v[64:65], 0, v[168:169]
	v_lshl_add_u64 v[64:65], v[86:87], 0, v[80:81]
	v_lshl_add_u64 v[136:137], v[66:67], 0, s[4:5]
	v_mov_b64_e32 v[66:67], s[40:41]
	global_load_dwordx2 v[132:133], v[64:65], off nt
	v_lshl_add_u64 v[64:65], v[88:89], 0, v[80:81]
	v_mad_i64_i32 v[66:67], s[4:5], v72, s88, v[66:67]
	global_load_dwordx2 v[130:131], v[64:65], off nt
	v_lshl_add_u64 v[64:65], v[90:91], 0, v[80:81]
	v_lshl_add_u64 v[138:139], v[66:67], 0, s[36:37]
	global_load_dwordx2 v[100:101], v[64:65], off nt
	v_lshl_add_u64 v[64:65], v[136:137], 0, v[80:81]
	v_lshl_add_u64 v[140:141], v[66:67], 0, s[8:9]
	global_load_dwordx2 v[96:97], v[64:65], off nt
	v_lshl_add_u64 v[64:65], v[138:139], 0, v[80:81]
	global_load_dwordx2 v[70:71], v[64:65], off nt
	v_lshl_add_u64 v[64:65], v[140:141], 0, v[80:81]
	global_load_dwordx2 v[66:67], v[64:65], off nt
	v_lshlrev_b32_e32 v64, 2, v74
	v_mov_b32_e32 v65, v169
	v_lshl_add_u64 v[68:69], v[84:85], 0, v[64:65]
	v_lshlrev_b32_e32 v64, 1, v74
	v_lshl_add_u64 v[92:93], v[86:87], 0, v[64:65]
	global_load_dwordx2 v[128:129], v[92:93], off nt
	v_lshl_add_u64 v[92:93], v[88:89], 0, v[64:65]
	global_load_dwordx2 v[126:127], v[92:93], off nt
	v_lshl_add_u64 v[92:93], v[90:91], 0, v[64:65]
	global_load_dwordx2 v[124:125], v[92:93], off nt
	v_lshl_add_u64 v[92:93], v[136:137], 0, v[64:65]
	global_load_dwordx2 v[122:123], v[92:93], off nt
	v_lshl_add_u64 v[92:93], v[138:139], 0, v[64:65]
	v_lshl_add_u64 v[64:65], v[140:141], 0, v[64:65]
	global_load_dwordx2 v[120:121], v[92:93], off nt
	global_load_dwordx2 v[118:119], v[64:65], off nt
	v_lshlrev_b32_e32 v64, 2, v76
	v_mov_b32_e32 v65, v169
	v_lshl_add_u64 v[116:117], v[84:85], 0, v[64:65]
	v_lshlrev_b32_e32 v64, 1, v76
	v_lshl_add_u64 v[92:93], v[86:87], 0, v[64:65]
	global_load_dwordx2 v[114:115], v[92:93], off nt
	v_lshl_add_u64 v[92:93], v[88:89], 0, v[64:65]
	global_load_dwordx2 v[112:113], v[92:93], off nt
	v_lshl_add_u64 v[92:93], v[90:91], 0, v[64:65]
	global_load_dwordx2 v[110:111], v[92:93], off nt
	v_lshl_add_u64 v[92:93], v[136:137], 0, v[64:65]
	global_load_dwordx2 v[108:109], v[92:93], off nt
	v_lshl_add_u64 v[92:93], v[138:139], 0, v[64:65]
	v_lshl_add_u64 v[64:65], v[140:141], 0, v[64:65]
	global_load_dwordx2 v[106:107], v[92:93], off nt
	global_load_dwordx2 v[104:105], v[64:65], off nt
	v_lshlrev_b32_e32 v64, 2, v78
	v_mov_b32_e32 v65, v169
	v_lshl_add_u64 v[98:99], v[84:85], 0, v[64:65]
	v_lshlrev_b32_e32 v64, 1, v78
	v_lshl_add_u64 v[134:135], v[84:85], 0, v[168:169]
	v_lshl_add_u64 v[84:85], v[86:87], 0, v[64:65]
	global_load_dwordx2 v[94:95], v[84:85], off nt
	v_lshl_add_u64 v[84:85], v[88:89], 0, v[64:65]
	global_load_dwordx2 v[92:93], v[84:85], off nt
	v_lshl_add_u64 v[84:85], v[90:91], 0, v[64:65]
	global_load_dwordx2 v[90:91], v[84:85], off nt
	v_lshl_add_u64 v[84:85], v[136:137], 0, v[64:65]
	global_load_dwordx2 v[88:89], v[84:85], off nt
	v_lshl_add_u64 v[84:85], v[138:139], 0, v[64:65]
	v_lshl_add_u64 v[64:65], v[140:141], 0, v[64:65]
	global_load_dwordx2 v[86:87], v[84:85], off nt
	s_waitcnt vmcnt(22)
	v_lshlrev_b32_e32 v77, 16, v132
	global_load_dwordx2 v[84:85], v[64:65], off nt
	global_load_dwordx4 v[136:139], v[102:103], off nt
	global_load_dwordx4 v[140:143], v[134:135], off nt
	v_lshlrev_b64 v[64:65], 11, v[72:73]
	v_and_b32_e32 v79, 0xffff0000, v132
	v_lshlrev_b32_e32 v132, 16, v133
	v_and_b32_e32 v133, 0xffff0000, v133
	v_add_u32_e32 v72, s6, v72
	s_waitcnt vmcnt(21)
	v_lshlrev_b32_e32 v144, 16, v70
	v_and_b32_e32 v70, 0xffff0000, v70
	s_waitcnt vmcnt(20)
	v_lshlrev_b32_e32 v146, 16, v66
	v_and_b32_e32 v66, 0xffff0000, v66
	v_add_f32_e32 v66, v70, v66
	v_lshlrev_b32_e32 v145, 16, v71
	v_and_b32_e32 v71, 0xffff0000, v71
	v_lshlrev_b32_e32 v147, 16, v67
	v_and_b32_e32 v67, 0xffff0000, v67
	v_add_f32_e32 v66, -2.0, v66
	v_fma_f32 v66, v1, v66, 2.0
	v_add_f32_e32 v70, v145, v147
	v_add_f32_e32 v67, v71, v67
	v_add_f32_e32 v70, -2.0, v70
	v_fma_f32 v70, v2, v70, 2.0
	v_add_f32_e32 v67, -2.0, v67
	v_fma_f32 v67, v3, v67, 2.0
	s_waitcnt vmcnt(0)
	v_pk_add_f32 v[136:137], v[136:137], v[140:141]
	v_pk_add_f32 v[134:135], v[138:139], v[142:143]
	v_add_f32_e32 v73, v136, v137
	v_add_f32_e32 v73, v73, v134
	v_add_f32_e32 v73, v73, v135
	v_lshlrev_b32_e32 v142, 16, v96
	v_mul_f32_e32 v71, 0xbfb8aa3b, v142
	v_add_f32_dpp v73, v73, v73 row_ror:8 row_mask:0xf bank_mask:0xf bound_ctrl:1
	v_exp_f32_e32 v71, v71
	v_and_b32_e32 v96, 0xffff0000, v96
	v_add_f32_dpp v73, v73, v73 row_ror:4 row_mask:0xf bank_mask:0xf bound_ctrl:1
	v_lshlrev_b32_e32 v143, 16, v97
	v_add_f32_e32 v71, 1.0, v71
	v_add_f32_dpp v73, v73, v73 row_ror:2 row_mask:0xf bank_mask:0xf bound_ctrl:1
	v_and_b32_e32 v97, 0xffff0000, v97
	s_nop 0
	v_add_f32_dpp v73, v73, v73 row_ror:1 row_mask:0xf bank_mask:0xf bound_ctrl:1
	v_mul_f32_e32 v138, 0x3c800000, v73
	v_pk_add_f32 v[136:137], v[136:137], v[138:139] op_sel_hi:[1,0] neg_lo:[0,1] neg_hi:[0,1]
	v_pk_add_f32 v[134:135], v[134:135], v[138:139] op_sel_hi:[1,0] neg_lo:[0,1] neg_hi:[0,1]
	v_pk_mul_f32 v[140:141], v[136:137], v[136:137]
	v_pk_mul_f32 v[138:139], v[134:135], v[134:135]
	v_add_f32_e32 v73, v140, v141
	v_add_f32_e32 v73, v138, v73
	v_add_f32_e32 v73, v139, v73
	v_lshlrev_b32_e32 v138, 16, v130
	v_mul_f32_e32 v77, v77, v138
	v_add_f32_dpp v73, v73, v73 row_ror:8 row_mask:0xf bank_mask:0xf bound_ctrl:1
	v_add_f32_e32 v138, v144, v146
	v_add_f32_e32 v138, -2.0, v138
	v_add_f32_dpp v73, v73, v73 row_ror:4 row_mask:0xf bank_mask:0xf bound_ctrl:1
	v_and_b32_e32 v130, 0xffff0000, v130
	v_fma_f32 v138, v0, v138, 2.0
	v_add_f32_dpp v73, v73, v73 row_ror:2 row_mask:0xf bank_mask:0xf bound_ctrl:1
	v_mul_f32_e32 v77, v77, v138
	v_mul_f32_e32 v79, v79, v130
	v_add_f32_dpp v73, v73, v73 row_ror:1 row_mask:0xf bank_mask:0xf bound_ctrl:1
	v_fmamk_f32 v73, v73, 0x3c800000, v213
	v_cmp_gt_f32_e32 vcc, s80, v73
	v_mul_f32_e32 v75, 0x4b800000, v73
	v_lshlrev_b32_e32 v139, 16, v131
	v_cndmask_b32_e32 v73, v73, v75, vcc
	v_rsq_f32_e32 v73, v73
	v_fma_f32 v77, v8, v77, 0
	v_mul_f32_e32 v66, v79, v66
	v_fmac_f32_e32 v77, v9, v66
	v_mul_f32_e32 v66, v132, v139
	v_and_b32_e32 v131, 0xffff0000, v131
	v_mul_f32_e32 v66, v66, v70
	v_fmac_f32_e32 v77, v10, v66
	v_mul_f32_e32 v66, v133, v131
	v_mul_f32_e32 v75, 0x45800000, v73
	v_mul_f32_e32 v66, v66, v67
	v_fmac_f32_e32 v77, v11, v66
	v_cndmask_b32_e32 v66, v73, v75, vcc
	s_nop 0
	v_add_f32_dpp v67, v77, v77 row_ror:8 row_mask:0xf bank_mask:0xf bound_ctrl:1
	v_mul_f32_e32 v70, v136, v66
	v_lshlrev_b32_e32 v140, 16, v100
	v_rcp_f32_e32 v71, v71
	s_nop 0
	v_mul_f32_e32 v73, 0xbfb8aa3b, v96
	v_exp_f32_e32 v73, v73
	v_add_f32_dpp v67, v67, v67 row_ror:4 row_mask:0xf bank_mask:0xf bound_ctrl:1
	v_fma_f32 v70, v16, v70, v24
	v_mul_f32_e32 v71, v71, v142
	v_add_f32_e32 v73, 1.0, v73
	v_add_f32_dpp v67, v67, v67 row_ror:2 row_mask:0xf bank_mask:0xf bound_ctrl:1
	v_and_b32_e32 v100, 0xffff0000, v100
	v_lshlrev_b32_e32 v141, 16, v101
	v_add_f32_dpp v67, v67, v67 row_ror:1 row_mask:0xf bank_mask:0xf bound_ctrl:1
	v_fmac_f32_e32 v70, v67, v140
	v_mul_f32_e32 v70, v71, v70
	v_mul_f32_e32 v71, v137, v66
	v_fma_f32 v71, v17, v71, v25
	v_fmac_f32_e32 v71, v67, v100
	v_rcp_f32_e32 v73, v73
	s_nop 0
	v_mul_f32_e32 v75, 0xbfb8aa3b, v143
	v_exp_f32_e32 v75, v75
	v_mul_f32_e32 v73, v73, v96
	v_mul_f32_e32 v71, v73, v71
	v_mul_f32_e32 v73, v134, v66
	v_add_f32_e32 v75, 1.0, v75
	v_mul_f32_e32 v66, v135, v66
	v_and_b32_e32 v101, 0xffff0000, v101
	v_fma_f32 v73, v18, v73, v26
	v_fma_f32 v66, v19, v66, v27
	v_fmac_f32_e32 v73, v67, v141
	v_fmac_f32_e32 v66, v67, v101
	v_mul_f32_e32 v67, 0xbfb8aa3b, v97
	v_exp_f32_e32 v67, v67
	v_rcp_f32_e32 v75, v75
	s_nop 0
	s_nop 0
	v_mul_f32_e32 v75, v75, v143
	v_add_f32_e32 v67, 1.0, v67
	v_mul_f32_e32 v73, v75, v73
	v_lshlrev_b32_e32 v132, 16, v120
	v_lshlrev_b32_e32 v134, 16, v118
	v_and_b32_e32 v120, 0xffff0000, v120
	v_rcp_f32_e32 v67, v67
	s_nop 0
	s_nop 0
	v_mul_f32_e32 v67, v67, v97
	v_mul_f32_e32 v66, v67, v66
	v_cvt_pk_bf16_f32 v100, v70, v71
	v_cvt_pk_bf16_f32 v101, v73, v66
	v_lshl_add_u64 v[96:97], v[82:83], 0, v[64:65]
	global_load_dwordx4 v[64:67], v[102:103], off offset:1024 nt
	s_nop 0
	global_load_dwordx4 v[68:71], v[68:69], off nt
	v_lshlrev_b32_e32 v77, 16, v126
	v_and_b32_e32 v118, 0xffff0000, v118
	v_and_b32_e32 v79, 0xffff0000, v126
	v_lshlrev_b32_e32 v73, 16, v129
	v_lshlrev_b32_e32 v126, 16, v127
	v_lshlrev_b32_e32 v133, 16, v121
	v_lshlrev_b32_e32 v135, 16, v119
	v_and_b32_e32 v121, 0xffff0000, v121
	v_and_b32_e32 v119, 0xffff0000, v119
	v_and_b32_e32 v75, 0xffff0000, v129
	v_and_b32_e32 v127, 0xffff0000, v127
	v_lshlrev_b32_e32 v130, 16, v122
	v_and_b32_e32 v122, 0xffff0000, v122
	v_lshlrev_b32_e32 v131, 16, v123
	v_and_b32_e32 v123, 0xffff0000, v123
	v_lshlrev_b32_e32 v129, 16, v125
	v_and_b32_e32 v125, 0xffff0000, v125
	s_waitcnt vmcnt(0)
	v_pk_add_f32 v[64:65], v[64:65], v[68:69]
	v_pk_add_f32 v[66:67], v[66:67], v[70:71]
	v_add_f32_e32 v68, v64, v65
	v_add_f32_e32 v68, v68, v66
	v_add_f32_e32 v68, v68, v67
	s_nop 1
	v_add_f32_dpp v68, v68, v68 row_ror:8 row_mask:0xf bank_mask:0xf bound_ctrl:1
	s_nop 1
	v_add_f32_dpp v68, v68, v68 row_ror:4 row_mask:0xf bank_mask:0xf bound_ctrl:1
	s_nop 1
	v_add_f32_dpp v68, v68, v68 row_ror:2 row_mask:0xf bank_mask:0xf bound_ctrl:1
	s_nop 1
	v_add_f32_dpp v68, v68, v68 row_ror:1 row_mask:0xf bank_mask:0xf bound_ctrl:1
	v_mul_f32_e32 v68, 0x3c800000, v68
	v_pk_add_f32 v[64:65], v[64:65], v[68:69] op_sel_hi:[1,0] neg_lo:[0,1] neg_hi:[0,1]
	v_pk_add_f32 v[66:67], v[66:67], v[68:69] op_sel_hi:[1,0] neg_lo:[0,1] neg_hi:[0,1]
	v_pk_mul_f32 v[70:71], v[64:65], v[64:65]
	v_pk_mul_f32 v[68:69], v[66:67], v[66:67]
	v_add_f32_e32 v70, v70, v71
	v_add_f32_e32 v68, v68, v70
	v_lshlrev_b32_e32 v70, 16, v128
	v_mul_f32_e32 v70, v70, v77
	v_add_f32_e32 v77, v132, v134
	v_add_f32_e32 v77, -2.0, v77
	v_add_f32_e32 v68, v69, v68
	v_fma_f32 v77, v4, v77, 2.0
	v_mul_f32_e32 v70, v70, v77
	v_add_f32_dpp v68, v68, v68 row_ror:8 row_mask:0xf bank_mask:0xf bound_ctrl:1
	v_add_f32_e32 v77, v120, v118
	v_and_b32_e32 v71, 0xffff0000, v128
	v_add_f32_dpp v68, v68, v68 row_ror:4 row_mask:0xf bank_mask:0xf bound_ctrl:1
	v_add_f32_e32 v77, -2.0, v77
	v_mul_f32_e32 v71, v71, v79
	v_add_f32_dpp v68, v68, v68 row_ror:2 row_mask:0xf bank_mask:0xf bound_ctrl:1
	v_fma_f32 v77, v5, v77, 2.0
	v_fma_f32 v70, v12, v70, 0
	v_add_f32_dpp v68, v68, v68 row_ror:1 row_mask:0xf bank_mask:0xf bound_ctrl:1
	v_mul_f32_e32 v71, v71, v77
	v_fmamk_f32 v68, v68, 0x3c800000, v213
	v_fmac_f32_e32 v70, v13, v71
	v_mul_f32_e32 v71, v73, v126
	v_add_f32_e32 v73, v133, v135
	v_cmp_gt_f32_e32 vcc, s80, v68
	v_mul_f32_e32 v69, 0x4b800000, v68
	v_add_f32_e32 v73, -2.0, v73
	v_cndmask_b32_e32 v68, v68, v69, vcc
	v_fma_f32 v73, v6, v73, 2.0
	v_rsq_f32_e32 v68, v68
	v_mul_f32_e32 v71, v71, v73
	v_add_f32_e32 v73, v121, v119
	v_add_f32_e32 v73, -2.0, v73
	v_fmac_f32_e32 v70, v14, v71
	v_mul_f32_e32 v71, v75, v127
	v_fma_f32 v73, v7, v73, 2.0
	v_mul_f32_e32 v71, v71, v73
	v_mul_f32_e32 v69, 0x45800000, v68
	v_fmac_f32_e32 v70, v15, v71
	v_cndmask_b32_e32 v68, v68, v69, vcc
	v_mul_f32_e32 v64, v64, v68
	v_add_f32_dpp v69, v70, v70 row_ror:8 row_mask:0xf bank_mask:0xf bound_ctrl:1
	v_mul_f32_e32 v70, 0xbfb8aa3b, v130
	v_exp_f32_e32 v70, v70
	v_add_f32_dpp v69, v69, v69 row_ror:4 row_mask:0xf bank_mask:0xf bound_ctrl:1
	v_lshlrev_b32_e32 v128, 16, v124
	v_fma_f32 v64, v20, v64, v28
	v_add_f32_e32 v70, 1.0, v70
	v_add_f32_dpp v69, v69, v69 row_ror:2 row_mask:0xf bank_mask:0xf bound_ctrl:1
	v_mul_f32_e32 v65, v65, v68
	v_and_b32_e32 v124, 0xffff0000, v124
	v_add_f32_dpp v69, v69, v69 row_ror:1 row_mask:0xf bank_mask:0xf bound_ctrl:1
	v_rcp_f32_e32 v70, v70
	s_nop 0
	v_fmac_f32_e32 v64, v69, v128
	v_mul_f32_e32 v70, v70, v130
	v_mul_f32_e32 v64, v70, v64
	v_mul_f32_e32 v70, 0xbfb8aa3b, v122
	v_exp_f32_e32 v70, v70
	v_fma_f32 v65, v21, v65, v29
	v_fmac_f32_e32 v65, v69, v124
	v_mul_f32_e32 v66, v66, v68
	v_add_f32_e32 v70, 1.0, v70
	v_mul_f32_e32 v67, v67, v68
	v_mul_f32_e32 v68, 0xbfb8aa3b, v123
	v_exp_f32_e32 v68, v68
	v_rcp_f32_e32 v70, v70
	s_nop 0
	s_nop 0
	v_mul_f32_e32 v70, v70, v122
	v_mul_f32_e32 v65, v70, v65
	v_mul_f32_e32 v70, 0xbfb8aa3b, v131
	v_exp_f32_e32 v70, v70
	v_fma_f32 v66, v22, v66, v30
	v_fma_f32 v67, v23, v67, v31
	v_add_f32_e32 v68, 1.0, v68
	v_add_f32_e32 v70, 1.0, v70
	v_fmac_f32_e32 v66, v69, v129
	v_fmac_f32_e32 v67, v69, v125
	v_rcp_f32_e32 v70, v70
	s_nop 0
	s_nop 0
	v_mul_f32_e32 v70, v70, v131
	v_mul_f32_e32 v66, v70, v66
	v_cvt_pk_bf16_f32 v118, v64, v65
	v_lshlrev_b32_e32 v77, 16, v112
	v_lshlrev_b32_e32 v120, 16, v106
	v_rcp_f32_e32 v68, v68
	s_nop 0
	s_nop 0
	v_mul_f32_e32 v68, v68, v123
	v_mul_f32_e32 v67, v68, v67
	v_cvt_pk_bf16_f32 v119, v66, v67
	global_load_dwordx4 v[64:67], v[102:103], off offset:2048 nt
	global_load_dwordx4 v[68:71], v[116:117], off nt
	v_lshlrev_b32_e32 v122, 16, v104
	v_and_b32_e32 v106, 0xffff0000, v106
	v_and_b32_e32 v104, 0xffff0000, v104
	v_and_b32_e32 v79, 0xffff0000, v112
	v_lshlrev_b32_e32 v73, 16, v115
	v_lshlrev_b32_e32 v112, 16, v113
	v_lshlrev_b32_e32 v121, 16, v107
	v_lshlrev_b32_e32 v123, 16, v105
	v_and_b32_e32 v107, 0xffff0000, v107
	v_and_b32_e32 v105, 0xffff0000, v105
	v_and_b32_e32 v75, 0xffff0000, v115
	v_and_b32_e32 v113, 0xffff0000, v113
	v_lshlrev_b32_e32 v116, 16, v108
	v_and_b32_e32 v108, 0xffff0000, v108
	v_lshlrev_b32_e32 v117, 16, v109
	v_and_b32_e32 v109, 0xffff0000, v109
	v_lshlrev_b32_e32 v115, 16, v111
	v_and_b32_e32 v111, 0xffff0000, v111
	s_waitcnt vmcnt(0)
	v_pk_add_f32 v[64:65], v[64:65], v[68:69]
	v_pk_add_f32 v[66:67], v[66:67], v[70:71]
	v_add_f32_e32 v68, v64, v65
	v_add_f32_e32 v68, v68, v66
	v_add_f32_e32 v68, v68, v67
	s_nop 1
	v_add_f32_dpp v68, v68, v68 row_ror:8 row_mask:0xf bank_mask:0xf bound_ctrl:1
	s_nop 1
	v_add_f32_dpp v68, v68, v68 row_ror:4 row_mask:0xf bank_mask:0xf bound_ctrl:1
	s_nop 1
	v_add_f32_dpp v68, v68, v68 row_ror:2 row_mask:0xf bank_mask:0xf bound_ctrl:1
	s_nop 1
	v_add_f32_dpp v68, v68, v68 row_ror:1 row_mask:0xf bank_mask:0xf bound_ctrl:1
	v_mul_f32_e32 v68, 0x3c800000, v68
	v_pk_add_f32 v[64:65], v[64:65], v[68:69] op_sel_hi:[1,0] neg_lo:[0,1] neg_hi:[0,1]
	v_pk_add_f32 v[66:67], v[66:67], v[68:69] op_sel_hi:[1,0] neg_lo:[0,1] neg_hi:[0,1]
	v_pk_mul_f32 v[70:71], v[64:65], v[64:65]
	v_pk_mul_f32 v[68:69], v[66:67], v[66:67]
	v_add_f32_e32 v70, v70, v71
	v_add_f32_e32 v68, v68, v70
	v_lshlrev_b32_e32 v70, 16, v114
	v_mul_f32_e32 v70, v70, v77
	v_add_f32_e32 v77, v120, v122
	v_add_f32_e32 v77, -2.0, v77
	v_add_f32_e32 v68, v69, v68
	v_fma_f32 v77, v32, v77, 2.0
	v_mul_f32_e32 v70, v70, v77
	v_add_f32_dpp v68, v68, v68 row_ror:8 row_mask:0xf bank_mask:0xf bound_ctrl:1
	v_add_f32_e32 v77, v106, v104
	v_and_b32_e32 v71, 0xffff0000, v114
	v_add_f32_dpp v68, v68, v68 row_ror:4 row_mask:0xf bank_mask:0xf bound_ctrl:1
	v_add_f32_e32 v77, -2.0, v77
	v_mul_f32_e32 v71, v71, v79
	v_add_f32_dpp v68, v68, v68 row_ror:2 row_mask:0xf bank_mask:0xf bound_ctrl:1
	v_fma_f32 v77, v33, v77, 2.0
	v_fma_f32 v70, v40, v70, 0
	v_add_f32_dpp v68, v68, v68 row_ror:1 row_mask:0xf bank_mask:0xf bound_ctrl:1
	v_mul_f32_e32 v71, v71, v77
	v_fmamk_f32 v68, v68, 0x3c800000, v213
	v_fmac_f32_e32 v70, v41, v71
	v_mul_f32_e32 v71, v73, v112
	v_add_f32_e32 v73, v121, v123
	v_cmp_gt_f32_e32 vcc, s80, v68
	v_mul_f32_e32 v69, 0x4b800000, v68
	v_add_f32_e32 v73, -2.0, v73
	v_cndmask_b32_e32 v68, v68, v69, vcc
	v_fma_f32 v73, v34, v73, 2.0
	v_rsq_f32_e32 v68, v68
	v_mul_f32_e32 v71, v71, v73
	v_add_f32_e32 v73, v107, v105
	v_add_f32_e32 v73, -2.0, v73
	v_fmac_f32_e32 v70, v42, v71
	v_mul_f32_e32 v71, v75, v113
	v_fma_f32 v73, v35, v73, 2.0
	v_mul_f32_e32 v71, v71, v73
	v_mul_f32_e32 v69, 0x45800000, v68
	v_fmac_f32_e32 v70, v43, v71
	v_cndmask_b32_e32 v68, v68, v69, vcc
	v_mul_f32_e32 v64, v64, v68
	v_add_f32_dpp v69, v70, v70 row_ror:8 row_mask:0xf bank_mask:0xf bound_ctrl:1
	v_mul_f32_e32 v70, 0xbfb8aa3b, v116
	v_exp_f32_e32 v70, v70
	v_add_f32_dpp v69, v69, v69 row_ror:4 row_mask:0xf bank_mask:0xf bound_ctrl:1
	v_lshlrev_b32_e32 v114, 16, v110
	v_fma_f32 v64, v48, v64, v56
	v_add_f32_e32 v70, 1.0, v70
	v_add_f32_dpp v69, v69, v69 row_ror:2 row_mask:0xf bank_mask:0xf bound_ctrl:1
	v_mul_f32_e32 v65, v65, v68
	v_and_b32_e32 v110, 0xffff0000, v110
	v_add_f32_dpp v69, v69, v69 row_ror:1 row_mask:0xf bank_mask:0xf bound_ctrl:1
	v_rcp_f32_e32 v70, v70
	s_nop 0
	v_fmac_f32_e32 v64, v69, v114
	v_mul_f32_e32 v70, v70, v116
	v_mul_f32_e32 v64, v70, v64
	v_mul_f32_e32 v70, 0xbfb8aa3b, v108
	v_exp_f32_e32 v70, v70
	v_fma_f32 v65, v49, v65, v57
	v_fmac_f32_e32 v65, v69, v110
	v_mul_f32_e32 v66, v66, v68
	v_add_f32_e32 v70, 1.0, v70
	v_mul_f32_e32 v67, v67, v68
	v_mul_f32_e32 v68, 0xbfb8aa3b, v109
	v_exp_f32_e32 v68, v68
	v_rcp_f32_e32 v70, v70
	s_nop 0
	s_nop 0
	v_mul_f32_e32 v70, v70, v108
	v_mul_f32_e32 v65, v70, v65
	v_mul_f32_e32 v70, 0xbfb8aa3b, v117
	v_exp_f32_e32 v70, v70
	v_fma_f32 v66, v50, v66, v58
	v_fma_f32 v67, v51, v67, v59
	v_add_f32_e32 v68, 1.0, v68
	v_add_f32_e32 v70, 1.0, v70
	v_fmac_f32_e32 v66, v69, v115
	v_fmac_f32_e32 v67, v69, v111
	v_rcp_f32_e32 v70, v70
	s_nop 0
	s_nop 0
	v_mul_f32_e32 v70, v70, v117
	v_mul_f32_e32 v66, v70, v66
	v_cvt_pk_bf16_f32 v104, v64, v65
	v_lshlrev_b32_e32 v77, 16, v92
	v_and_b32_e32 v79, 0xffff0000, v92
	v_rcp_f32_e32 v68, v68
	s_nop 0
	s_nop 0
	v_mul_f32_e32 v68, v68, v109
	v_mul_f32_e32 v67, v68, v67
	v_cvt_pk_bf16_f32 v105, v66, v67
	global_load_dwordx4 v[64:67], v[102:103], off offset:3072 nt
	global_load_dwordx4 v[68:71], v[98:99], off nt
	s_nop 0
	global_store_dwordx2 v[96:97], v[100:101], off
	global_store_dwordx2 v[96:97], v[118:119], off offset:512
	global_store_dwordx2 v[96:97], v[104:105], off offset:1024
	v_lshlrev_b32_e32 v100, 16, v86
	v_lshlrev_b32_e32 v102, 16, v84
	v_and_b32_e32 v86, 0xffff0000, v86
	v_and_b32_e32 v84, 0xffff0000, v84
	v_lshlrev_b32_e32 v73, 16, v95
	v_lshlrev_b32_e32 v92, 16, v93
	v_lshlrev_b32_e32 v101, 16, v87
	v_lshlrev_b32_e32 v103, 16, v85
	v_and_b32_e32 v87, 0xffff0000, v87
	v_and_b32_e32 v85, 0xffff0000, v85
	v_and_b32_e32 v75, 0xffff0000, v95
	v_and_b32_e32 v93, 0xffff0000, v93
	v_lshlrev_b32_e32 v95, 16, v91
	v_and_b32_e32 v91, 0xffff0000, v91
	s_waitcnt vmcnt(3)
	v_pk_add_f32 v[64:65], v[64:65], v[68:69]
	v_pk_add_f32 v[66:67], v[66:67], v[70:71]
	v_add_f32_e32 v68, v64, v65
	v_add_f32_e32 v68, v68, v66
	v_add_f32_e32 v68, v68, v67
	s_nop 1
	v_add_f32_dpp v68, v68, v68 row_ror:8 row_mask:0xf bank_mask:0xf bound_ctrl:1
	s_nop 1
	v_add_f32_dpp v68, v68, v68 row_ror:4 row_mask:0xf bank_mask:0xf bound_ctrl:1
	s_nop 1
	v_add_f32_dpp v68, v68, v68 row_ror:2 row_mask:0xf bank_mask:0xf bound_ctrl:1
	s_nop 1
	v_add_f32_dpp v68, v68, v68 row_ror:1 row_mask:0xf bank_mask:0xf bound_ctrl:1
	v_mul_f32_e32 v68, 0x3c800000, v68
	v_pk_add_f32 v[70:71], v[64:65], v[68:69] op_sel_hi:[1,0] neg_lo:[0,1] neg_hi:[0,1]
	v_pk_add_f32 v[64:65], v[66:67], v[68:69] op_sel_hi:[1,0] neg_lo:[0,1] neg_hi:[0,1]
	v_pk_mul_f32 v[98:99], v[70:71], v[70:71]
	v_pk_mul_f32 v[66:67], v[64:65], v[64:65]
	v_add_f32_e32 v68, v98, v99
	v_add_f32_e32 v66, v66, v68
	v_lshlrev_b32_e32 v68, 16, v94
	v_mul_f32_e32 v68, v68, v77
	v_add_f32_e32 v77, v100, v102
	v_add_f32_e32 v77, -2.0, v77
	v_fma_f32 v77, v36, v77, 2.0
	v_mul_f32_e32 v68, v68, v77
	v_add_f32_e32 v77, v86, v84
	v_and_b32_e32 v69, 0xffff0000, v94
	v_add_f32_e32 v77, -2.0, v77
	v_mul_f32_e32 v69, v69, v79
	v_fma_f32 v77, v37, v77, 2.0
	v_add_f32_e32 v66, v67, v66
	v_fma_f32 v68, v44, v68, 0
	v_mul_f32_e32 v69, v69, v77
	v_add_f32_dpp v66, v66, v66 row_ror:8 row_mask:0xf bank_mask:0xf bound_ctrl:1
	v_fmac_f32_e32 v68, v45, v69
	v_mul_f32_e32 v69, v73, v92
	v_add_f32_e32 v73, v101, v103
	v_add_f32_dpp v66, v66, v66 row_ror:4 row_mask:0xf bank_mask:0xf bound_ctrl:1
	v_add_f32_e32 v73, -2.0, v73
	v_fma_f32 v73, v38, v73, 2.0
	v_add_f32_dpp v66, v66, v66 row_ror:2 row_mask:0xf bank_mask:0xf bound_ctrl:1
	v_mul_f32_e32 v69, v69, v73
	v_add_f32_e32 v73, v87, v85
	v_add_f32_dpp v66, v66, v66 row_ror:1 row_mask:0xf bank_mask:0xf bound_ctrl:1
	v_fmamk_f32 v66, v66, 0x3c800000, v213
	v_add_f32_e32 v73, -2.0, v73
	v_cmp_gt_f32_e32 vcc, s80, v66
	v_mul_f32_e32 v67, 0x4b800000, v66
	v_fmac_f32_e32 v68, v46, v69
	v_mul_f32_e32 v69, v75, v93
	v_fma_f32 v73, v39, v73, 2.0
	v_cndmask_b32_e32 v66, v66, v67, vcc
	v_lshlrev_b32_e32 v98, 16, v88
	v_mul_f32_e32 v69, v69, v73
	v_rsq_f32_e32 v66, v66
	v_fmac_f32_e32 v68, v47, v69
	v_mul_f32_e32 v69, 0xbfb8aa3b, v98
	v_exp_f32_e32 v69, v69
	v_mul_f32_e32 v67, 0x45800000, v66
	v_cndmask_b32_e32 v66, v66, v67, vcc
	v_and_b32_e32 v88, 0xffff0000, v88
	v_add_f32_e32 v69, 1.0, v69
	v_add_f32_dpp v67, v68, v68 row_ror:8 row_mask:0xf bank_mask:0xf bound_ctrl:1
	v_mul_f32_e32 v68, v70, v66
	s_nop 0
	v_add_f32_dpp v67, v67, v67 row_ror:4 row_mask:0xf bank_mask:0xf bound_ctrl:1
	v_lshlrev_b32_e32 v94, 16, v90
	v_fma_f32 v68, v52, v68, v60
	v_rcp_f32_e32 v69, v69
	s_nop 0
	v_mul_f32_e32 v70, 0xbfb8aa3b, v88
	v_exp_f32_e32 v70, v70
	v_add_f32_dpp v67, v67, v67 row_ror:2 row_mask:0xf bank_mask:0xf bound_ctrl:1
	v_mul_f32_e32 v69, v69, v98
	v_and_b32_e32 v90, 0xffff0000, v90
	v_add_f32_dpp v67, v67, v67 row_ror:1 row_mask:0xf bank_mask:0xf bound_ctrl:1
	v_fmac_f32_e32 v68, v67, v94
	v_add_f32_e32 v70, 1.0, v70
	v_mul_f32_e32 v68, v69, v68
	v_mul_f32_e32 v69, v71, v66
	v_fma_f32 v69, v53, v69, v61
	v_lshlrev_b32_e32 v99, 16, v89
	v_fmac_f32_e32 v69, v67, v90
	v_rcp_f32_e32 v70, v70
	s_nop 0
	s_nop 0
	v_mul_f32_e32 v70, v70, v88
	v_mul_f32_e32 v69, v70, v69
	v_mul_f32_e32 v70, 0xbfb8aa3b, v99
	v_exp_f32_e32 v70, v70
	v_mul_f32_e32 v64, v64, v66
	v_fma_f32 v64, v54, v64, v62
	v_and_b32_e32 v89, 0xffff0000, v89
	v_add_f32_e32 v70, 1.0, v70
	v_div_scale_f32 v71, s[4:5], v70, v70, 1.0
	v_rcp_f32_e32 v73, v71
	v_fmac_f32_e32 v64, v67, v95
	v_fma_f32 v75, -v71, v73, 1.0
	v_fmac_f32_e32 v73, v75, v73
	v_div_scale_f32 v75, vcc, 1.0, v70, 1.0
	v_mul_f32_e32 v77, v75, v73
	v_fma_f32 v79, -v71, v77, v75
	v_fmac_f32_e32 v77, v79, v73
	v_rcp_f32_e32 v70, v70
	s_nop 0
	s_nop 0
	v_mul_f32_e32 v70, v70, v99
	v_mul_f32_e32 v70, v70, v64
	v_mul_f32_e32 v64, v65, v66
	v_mul_f32_e32 v65, 0xbfb8aa3b, v89
	v_exp_f32_e32 v65, v65
	v_fma_f32 v64, v55, v64, v63
	v_fmac_f32_e32 v64, v67, v91
	v_add_f32_e32 v65, 1.0, v65
	v_div_scale_f32 v66, s[4:5], v65, v65, 1.0
	v_rcp_f32_e32 v67, v66
	s_nop 0
	v_fma_f32 v71, -v66, v67, 1.0
	v_fmac_f32_e32 v67, v71, v67
	v_div_scale_f32 v71, vcc, 1.0, v65, 1.0
	v_mul_f32_e32 v73, v71, v67
	v_fma_f32 v75, -v66, v73, v71
	v_fmac_f32_e32 v73, v75, v67
	v_fma_f32 v66, -v66, v73, v71
	v_div_fmas_f32 v66, v66, v67, v73
	v_rcp_f32_e32 v65, v65
	s_nop 0
	s_nop 0
	v_mul_f32_e32 v65, v65, v89
	v_cmp_lt_i32_e32 vcc, s7, v72
	v_mul_f32_e32 v65, v65, v64
	s_or_b64 s[42:43], vcc, s[42:43]
	v_cvt_pk_bf16_f32 v64, v68, v69
	v_cvt_pk_bf16_f32 v65, v70, v65
	global_store_dwordx2 v[96:97], v[64:65], off offset:1536
	s_andn2_b64 exec, exec, s[42:43]
	s_cbranch_execnz .LBB0_521

.LBB0_893:
	v_ashrrev_i32_e32 v97, 31, v96
	v_lshlrev_b64 v[32:33], 13, v[96:97]
	v_lshl_add_u64 v[108:109], v[98:99], 0, v[32:33]
	v_add_u32_e32 v32, 1, v96
	v_add_co_u32_e32 v106, vcc, s3, v108
	v_ashrrev_i32_e32 v33, 31, v32
	s_nop 0
	v_addc_co_u32_e32 v107, vcc, 0, v109, vcc
	v_lshlrev_b64 v[32:33], 13, v[32:33]
	global_load_dwordx4 v[76:79], v[108:109], off nt
	global_load_dwordx4 v[72:75], v[108:109], off offset:1024 nt
	global_load_dwordx4 v[56:59], v[106:107], off nt
	global_load_dwordx4 v[44:47], v[106:107], off offset:1024 nt
	global_load_dwordx4 v[64:67], v[106:107], off offset:2048 nt
	global_load_dwordx4 v[40:43], v[106:107], off offset:3072 nt
	v_lshl_add_u64 v[104:105], v[98:99], 0, v[32:33]
	global_load_dwordx4 v[60:63], v[104:105], off nt
	global_load_dwordx4 v[48:51], v[104:105], off offset:1024 nt
	v_add_co_u32_e32 v102, vcc, s3, v104
	v_add_u32_e32 v96, s4, v96
	s_nop 0
	v_addc_co_u32_e32 v103, vcc, 0, v105, vcc
	global_load_dwordx4 v[36:39], v[102:103], off nt
	global_load_dwordx4 v[32:35], v[102:103], off offset:1024 nt
	global_load_dwordx4 v[68:71], v[104:105], off offset:2048 nt
	global_load_dwordx4 v[92:95], v[108:109], off offset:2048 nt
	global_load_dwordx4 v[52:55], v[104:105], off offset:3072 nt
	global_load_dwordx4 v[88:91], v[108:109], off offset:3072 nt
	global_load_dwordx4 v[84:87], v[102:103], off offset:2048 nt
	global_load_dwordx4 v[80:83], v[102:103], off offset:3072 nt
	s_waitcnt vmcnt(13)
	v_mov_b32_e32 v134, v57
	s_waitcnt vmcnt(12)
	v_mov_b32_e32 v135, v45
	s_waitcnt vmcnt(11)
	v_mov_b32_e32 v142, v65
	s_waitcnt vmcnt(10)
	v_mov_b32_e32 v143, v41
	v_mov_b32_e32 v119, v77
	v_mov_b32_e32 v127, v73
	v_mov_b32_e32 v132, v56
	v_mov_b32_e32 v133, v44
	v_mov_b32_e32 v140, v64
	v_mov_b32_e32 v141, v40
	s_waitcnt vmcnt(9)
	v_mov_b32_e32 v118, v61
	s_waitcnt vmcnt(8)
	v_mov_b32_e32 v126, v49
	v_pk_mul_f32 v[134:135], v[134:135], v[134:135]
	v_pk_mul_f32 v[142:143], v[142:143], v[142:143]
	s_waitcnt vmcnt(7)
	v_mov_b32_e32 v150, v37
	s_waitcnt vmcnt(6)
	v_mov_b32_e32 v151, v33
	v_mov_b32_e32 v117, v76
	v_mov_b32_e32 v125, v72
	v_mov_b32_e32 v136, v58
	v_mov_b32_e32 v137, v46
	v_mov_b32_e32 v144, v66
	v_mov_b32_e32 v145, v42
	v_mov_b32_e32 v116, v60
	v_mov_b32_e32 v124, v48
	v_mov_b32_e32 v148, v36
	v_mov_b32_e32 v149, v32
	v_pk_mul_f32 v[118:119], v[118:119], v[118:119]
	v_pk_mul_f32 v[126:127], v[126:127], v[126:127]
	v_pk_fma_f32 v[132:133], v[132:133], v[132:133], v[134:135]
	v_pk_fma_f32 v[134:135], v[140:141], v[140:141], v[142:143]
	v_pk_mul_f32 v[140:141], v[150:151], v[150:151]
	v_mov_b32_e32 v121, v78
	v_mov_b32_e32 v129, v74
	v_mov_b32_e32 v138, v59
	v_mov_b32_e32 v139, v47
	v_mov_b32_e32 v146, v67
	v_mov_b32_e32 v147, v43
	v_mov_b32_e32 v120, v62
	v_mov_b32_e32 v128, v50
	v_mov_b32_e32 v152, v38
	v_mov_b32_e32 v153, v34
	v_pk_fma_f32 v[116:117], v[116:117], v[116:117], v[118:119]
	v_pk_fma_f32 v[118:119], v[124:125], v[124:125], v[126:127]
	v_pk_fma_f32 v[124:125], v[136:137], v[136:137], v[132:133]
	v_pk_fma_f32 v[126:127], v[144:145], v[144:145], v[134:135]
	v_pk_fma_f32 v[132:133], v[148:149], v[148:149], v[140:141]
	v_mov_b32_e32 v123, v79
	v_mov_b32_e32 v131, v75
	v_mov_b32_e32 v122, v63
	v_mov_b32_e32 v130, v51
	v_mov_b32_e32 v154, v39
	v_mov_b32_e32 v155, v35
	v_pk_fma_f32 v[116:117], v[120:121], v[120:121], v[116:117]
	v_pk_fma_f32 v[118:119], v[128:129], v[128:129], v[118:119]
	v_pk_fma_f32 v[120:121], v[138:139], v[138:139], v[124:125]
	v_pk_fma_f32 v[124:125], v[146:147], v[146:147], v[126:127]
	v_pk_fma_f32 v[126:127], v[152:153], v[152:153], v[132:133]
	v_pk_fma_f32 v[116:117], v[122:123], v[122:123], v[116:117]
	v_pk_fma_f32 v[122:123], v[154:155], v[154:155], v[126:127]
	v_pk_fma_f32 v[118:119], v[130:131], v[130:131], v[118:119]
	s_waitcnt vmcnt(5)
	v_mov_b32_e32 v126, v69
	s_waitcnt vmcnt(4)
	v_mov_b32_e32 v127, v93
	v_pk_add_f32 v[116:117], v[116:117], v[118:119]
	v_mov_b32_e32 v118, v68
	v_mov_b32_e32 v119, v92
	v_pk_mul_f32 v[126:127], v[126:127], v[126:127]
	v_mov_b32_e32 v128, v71
	v_pk_fma_f32 v[118:119], v[118:119], v[118:119], v[126:127]
	v_mov_b32_e32 v126, v70
	v_mov_b32_e32 v127, v94
	v_mov_b32_e32 v129, v95
	v_pk_fma_f32 v[118:119], v[126:127], v[126:127], v[118:119]
	s_waitcnt vmcnt(3)
	v_mov_b32_e32 v126, v53
	v_pk_fma_f32 v[118:119], v[128:129], v[128:129], v[118:119]
	s_waitcnt vmcnt(2)
	v_mov_b32_e32 v127, v89
	v_pk_add_f32 v[116:117], v[116:117], v[118:119]
	v_mov_b32_e32 v118, v52
	v_mov_b32_e32 v119, v88
	v_pk_mul_f32 v[126:127], v[126:127], v[126:127]
	v_mov_b32_e32 v128, v55
	v_pk_fma_f32 v[118:119], v[118:119], v[118:119], v[126:127]
	v_mov_b32_e32 v126, v54
	v_mov_b32_e32 v127, v90
	v_mov_b32_e32 v129, v91
	v_pk_fma_f32 v[118:119], v[126:127], v[126:127], v[118:119]
	s_waitcnt vmcnt(1)
	v_mov_b32_e32 v126, v85
	v_pk_fma_f32 v[118:119], v[128:129], v[128:129], v[118:119]
	s_waitcnt vmcnt(0)
	v_mov_b32_e32 v127, v81
	v_pk_add_f32 v[116:117], v[116:117], v[118:119]
	v_mov_b32_e32 v118, v122
	v_mov_b32_e32 v119, v120
	v_pk_add_f32 v[116:117], v[116:117], v[118:119]
	v_mov_b32_e32 v118, v84
	v_mov_b32_e32 v119, v80
	v_pk_mul_f32 v[126:127], v[126:127], v[126:127]
	v_mov_b32_e32 v128, v87
	v_pk_fma_f32 v[118:119], v[118:119], v[118:119], v[126:127]
	v_mov_b32_e32 v126, v86
	v_mov_b32_e32 v127, v82
	v_mov_b32_e32 v129, v83
	v_pk_fma_f32 v[118:119], v[126:127], v[126:127], v[118:119]
	v_mov_b32_e32 v120, v123
	v_pk_fma_f32 v[118:119], v[128:129], v[128:129], v[118:119]
	v_pk_add_f32 v[116:117], v[116:117], v[120:121]
	v_mov_b32_e32 v120, v118
	v_mov_b32_e32 v121, v124
	v_pk_add_f32 v[116:117], v[116:117], v[120:121]
	v_mov_b32_e32 v124, v119
	v_pk_add_f32 v[116:117], v[116:117], v[124:125]
	ds_bpermute_b32 v119, v101, v117
	ds_bpermute_b32 v118, v101, v116
	s_waitcnt lgkmcnt(0)
	v_pk_add_f32 v[116:117], v[116:117], v[118:119]
	ds_bpermute_b32 v119, v110, v117
	ds_bpermute_b32 v118, v110, v116
	s_waitcnt lgkmcnt(0)
	v_pk_add_f32 v[116:117], v[116:117], v[118:119]
	ds_bpermute_b32 v119, v111, v117
	ds_bpermute_b32 v118, v111, v116
	s_waitcnt lgkmcnt(0)
	v_pk_add_f32 v[116:117], v[116:117], v[118:119]
	ds_bpermute_b32 v119, v112, v117
	ds_bpermute_b32 v118, v112, v116
	s_waitcnt lgkmcnt(0)
	v_pk_add_f32 v[116:117], v[116:117], v[118:119]
	ds_bpermute_b32 v119, v113, v117
	ds_bpermute_b32 v118, v113, v116
	s_waitcnt lgkmcnt(0)
	v_pk_add_f32 v[116:117], v[116:117], v[118:119]
	ds_bpermute_b32 v119, v114, v117
	ds_bpermute_b32 v118, v114, v116
	s_waitcnt lgkmcnt(0)
	v_pk_add_f32 v[116:117], v[116:117], v[118:119]
	s_nop 0
	v_pk_fma_f32 v[116:117], v[116:117], s[2:3], v[100:101] op_sel_hi:[1,0,0]
	s_nop 0
	v_mul_f32_e32 v97, 0x4b800000, v117
	v_cmp_gt_f32_e32 vcc, s5, v117
	s_nop 1
	v_cndmask_b32_e32 v97, v117, v97, vcc
	v_rsq_f32_e32 v97, v97
	s_nop 0
	v_mul_f32_e32 v115, 0x45800000, v97
	v_cndmask_b32_e32 v118, v97, v115, vcc
	v_pk_mul_f32 v[44:45], v[44:45], v[118:119] op_sel_hi:[1,0]
	v_pk_mul_f32 v[46:47], v[46:47], v[118:119] op_sel_hi:[1,0]
	v_pk_mul_f32 v[44:45], v[20:21], v[44:45]
	v_pk_mul_f32 v[46:47], v[22:23], v[46:47]
	global_store_dwordx4 v[106:107], v[44:47], off offset:1024 nt
	v_cmp_gt_f32_e32 vcc, s5, v116
	v_pk_mul_f32 v[40:41], v[40:41], v[118:119] op_sel_hi:[1,0]
	v_pk_mul_f32 v[44:45], v[64:65], v[118:119] op_sel_hi:[1,0]
	v_pk_mul_f32 v[46:47], v[66:67], v[118:119] op_sel_hi:[1,0]
	v_pk_mul_f32 v[44:45], v[24:25], v[44:45]
	v_pk_mul_f32 v[46:47], v[26:27], v[46:47]
	global_store_dwordx4 v[106:107], v[44:47], off offset:2048 nt
	v_pk_mul_f32 v[42:43], v[42:43], v[118:119] op_sel_hi:[1,0]
	v_pk_mul_f32 v[40:41], v[28:29], v[40:41]
	v_mul_f32_e32 v44, 0x4b800000, v116
	v_cndmask_b32_e32 v44, v116, v44, vcc
	v_rsq_f32_e32 v44, v44
	v_pk_mul_f32 v[42:43], v[30:31], v[42:43]
	global_store_dwordx4 v[106:107], v[40:43], off offset:3072 nt
	v_pk_mul_f32 v[72:73], v[72:73], v[118:119] op_sel_hi:[1,0]
	v_pk_mul_f32 v[74:75], v[74:75], v[118:119] op_sel_hi:[1,0]
	v_mul_f32_e32 v40, 0x45800000, v44
	v_cndmask_b32_e32 v44, v44, v40, vcc
	v_pk_mul_f32 v[40:41], v[60:61], v[44:45] op_sel_hi:[1,0]
	v_pk_mul_f32 v[42:43], v[62:63], v[44:45] op_sel_hi:[1,0]
	v_pk_mul_f32 v[40:41], v[0:1], v[40:41]
	v_pk_mul_f32 v[42:43], v[2:3], v[42:43]
	global_store_dwordx4 v[104:105], v[40:43], off nt
	v_pk_mul_f32 v[32:33], v[32:33], v[44:45] op_sel_hi:[1,0]
	v_pk_mul_f32 v[34:35], v[34:35], v[44:45] op_sel_hi:[1,0]
	v_pk_mul_f32 v[40:41], v[48:49], v[44:45] op_sel_hi:[1,0]
	v_pk_mul_f32 v[42:43], v[50:51], v[44:45] op_sel_hi:[1,0]
	v_pk_mul_f32 v[72:73], v[4:5], v[72:73]
	v_pk_mul_f32 v[74:75], v[6:7], v[74:75]
	v_pk_mul_f32 v[40:41], v[4:5], v[40:41]
	v_pk_mul_f32 v[42:43], v[6:7], v[42:43]
	v_pk_mul_f32 v[32:33], v[20:21], v[32:33]
	v_pk_mul_f32 v[34:35], v[22:23], v[34:35]
	global_store_dwordx4 v[108:109], v[72:75], off offset:1024 nt
	global_store_dwordx4 v[104:105], v[40:43], off offset:1024 nt
	global_store_dwordx4 v[102:103], v[32:35], off offset:1024 nt
	v_pk_mul_f32 v[72:73], v[92:93], v[118:119] op_sel_hi:[1,0]
	v_pk_mul_f32 v[74:75], v[94:95], v[118:119] op_sel_hi:[1,0]
	v_pk_mul_f32 v[40:41], v[68:69], v[44:45] op_sel_hi:[1,0]
	v_pk_mul_f32 v[42:43], v[70:71], v[44:45] op_sel_hi:[1,0]
	v_pk_mul_f32 v[32:33], v[84:85], v[44:45] op_sel_hi:[1,0]
	v_pk_mul_f32 v[34:35], v[86:87], v[44:45] op_sel_hi:[1,0]
	v_pk_mul_f32 v[72:73], v[8:9], v[72:73]
	v_pk_mul_f32 v[74:75], v[10:11], v[74:75]
	v_pk_mul_f32 v[40:41], v[8:9], v[40:41]
	v_pk_mul_f32 v[42:43], v[10:11], v[42:43]
	v_pk_mul_f32 v[32:33], v[24:25], v[32:33]
	v_pk_mul_f32 v[34:35], v[26:27], v[34:35]
	v_pk_mul_f32 v[76:77], v[76:77], v[118:119] op_sel_hi:[1,0]
	v_pk_mul_f32 v[78:79], v[78:79], v[118:119] op_sel_hi:[1,0]
	global_store_dwordx4 v[108:109], v[72:75], off offset:2048 nt
	v_pk_mul_f32 v[56:57], v[56:57], v[118:119] op_sel_hi:[1,0]
	v_pk_mul_f32 v[58:59], v[58:59], v[118:119] op_sel_hi:[1,0]
	v_pk_mul_f32 v[72:73], v[88:89], v[118:119] op_sel_hi:[1,0]
	v_pk_mul_f32 v[74:75], v[90:91], v[118:119] op_sel_hi:[1,0]
	global_store_dwordx4 v[104:105], v[40:43], off offset:2048 nt
	v_pk_mul_f32 v[36:37], v[36:37], v[44:45] op_sel_hi:[1,0]
	v_pk_mul_f32 v[38:39], v[38:39], v[44:45] op_sel_hi:[1,0]
	v_pk_mul_f32 v[40:41], v[52:53], v[44:45] op_sel_hi:[1,0]
	v_pk_mul_f32 v[42:43], v[54:55], v[44:45] op_sel_hi:[1,0]
	global_store_dwordx4 v[102:103], v[32:35], off offset:2048 nt
	v_cmp_lt_i32_e32 vcc, s6, v96
	v_pk_mul_f32 v[76:77], v[0:1], v[76:77]
	v_pk_mul_f32 v[32:33], v[80:81], v[44:45] op_sel_hi:[1,0]
	v_pk_mul_f32 v[34:35], v[82:83], v[44:45] op_sel_hi:[1,0]
	v_pk_mul_f32 v[78:79], v[2:3], v[78:79]
	v_pk_mul_f32 v[72:73], v[12:13], v[72:73]
	v_pk_mul_f32 v[74:75], v[14:15], v[74:75]
	v_pk_mul_f32 v[56:57], v[16:17], v[56:57]
	v_pk_mul_f32 v[58:59], v[18:19], v[58:59]
	v_pk_mul_f32 v[40:41], v[12:13], v[40:41]
	v_pk_mul_f32 v[42:43], v[14:15], v[42:43]
	v_pk_mul_f32 v[36:37], v[16:17], v[36:37]
	v_pk_mul_f32 v[38:39], v[18:19], v[38:39]
	v_pk_mul_f32 v[32:33], v[28:29], v[32:33]
	v_pk_mul_f32 v[34:35], v[30:31], v[34:35]
	s_or_b64 s[0:1], vcc, s[0:1]
	global_store_dwordx4 v[108:109], v[76:79], off nt
	global_store_dwordx4 v[108:109], v[72:75], off offset:3072 nt
	global_store_dwordx4 v[106:107], v[56:59], off nt
	global_store_dwordx4 v[104:105], v[40:43], off offset:3072 nt
	global_store_dwordx4 v[102:103], v[36:39], off nt
	global_store_dwordx4 v[102:103], v[32:35], off offset:3072 nt
	s_andn2_b64 exec, exec, s[0:1]
	s_cbranch_execnz .LBB0_893
